# removed startup cg grid sync; skip redundant first accumulator zeroing in 13 GEMM unit loops
# speedup vs baseline: 1.0093x; 1.0093x over previous
; #define LAS __attribute__((address_space(3)))
; __device__ __forceinline__ unsigned xb_add(unsigned* p, unsigned v) { return __hip_atomic_fetch_add(p, v, __ATOMIC_RELAXED, __HIP_MEMORY_SCOPE_AGENT); }
; __device__ __forceinline__ unsigned xb_xcc_id() { return (unsigned)__builtin_amdgcn_s_getreg((3 << 11) | 20) & 0xFu; }
; #define IN(k) (((PHMASK >> (k)) & 1u) && phase_in(lo, hi, (k)))
; #define REP(k) for (int rep_ = 0, nrep_ = phase_rep(k); rep_ < nrep_; ++rep_)
; __global__ void __launch_bounds__(512, 2) mk_fwd(Args args) {
;     ...
;     if (hi - lo > 1) {
;         if (threadIdx.x == 0) (void)xb_add(&((unsigned*)args.ws)[XB_XCNT(xb_xcc_id())], 1u);
;         cg::this_grid().sync();
;     }
;     __syncthreads();
;     unsigned nbar = 0;
;     if (IN(0)) REP(0) {
;         PHASE_BEGIN;
;         const int lane = tid & 63, wave = __builtin_amdgcn_readfirstlane(tid >> 6);
;         LAS float* scr = (LAS float*)(lds + wave * 16384);
.LBB0_6:
	s_or_b64 exec, exec, s[2:3]
.LBB0_17:
	s_mov_b32 s2, s94
	s_mov_b32 s4, s95
	s_barrier
	s_cmp_lt_i32 s2, 1
	s_cselect_b64 s[2:3], -1, 0
	s_cmp_gt_i32 s4, 0
	s_cselect_b64 s[4:5], -1, 0
	s_and_b64 s[2:3], s[2:3], s[4:5]
	s_andn2_b64 vcc, exec, s[2:3]
	s_cbranch_vccnz .LBB0_197
	s_load_dwordx4 s[12:15], s[0:1], 0xe8
	s_mov_b32 s58, s78
	s_and_b32 s2, s92, 7
	s_waitcnt lgkmcnt(0)
	s_cmp_lg_u32 s2, 0
	s_mov_b32 s33, s58
	v_mbcnt_lo_u32_b32 v65, -1, 0
	v_mbcnt_hi_u32_b32 v65, -1, v65
	s_cbranch_scc1 .LBB0_20
	s_ashr_i32 s3, s58, 31
	s_lshr_b32 s3, s3, 29
	s_add_i32 s3, s58, s3
	s_ashr_i32 s4, s3, 3
	s_and_b32 s3, s3, -8
	s_ashr_i32 s2, s92, 3
	s_sub_i32 s3, s58, s3
	s_mul_i32 s2, s3, s2
	s_add_i32 s33, s2, s4

; template <class Epi>
; __device__ __forceinline__ void gemm_phase(LAS unsigned char* lds, const int tid, const Gemm g, const StaticOrder& S, const Epi& E) {
;     ...
;         const bool has_next = S.next(ui + 1, nxt);
;         const char* nA = has_next ? (const char*)g.A + (size_t)nxt.pm * tstepA + (size_t)(nxt.pn >> g.a_grp_shift) * g.a_grp_bytes : cA;
;         const char* nB = has_next ? (const char*)g.Bt + (size_t)nxt.pn * tstepB : cB;
;         for (int t = 0; t < nt; t += 2) {
;             const bool last = (t == nt - 2);
;             const char* a1 = cA + (size_t)(t + 1) * kstep;
;             const char* a2 = last ? nA : cA + (size_t)(t + 2) * kstep; const char* b2 = last ? nB : cB + (size_t)(t + 2) * kstep;
;             const char* a3 = a2 + kstep; const char* b3 = b2 + kstep;
;             if constexpr (Epi::SS_LDS) { if (last) {
;                 const char* sp = (const char*)E.ss + (size_t)cur.pm * (256 * 64) + (size_t)tid * 16;
;     ...
; #pragma unroll
;         for (int a = 0; a < 2; ++a)
; #pragma unroll
;             for (int b = 0; b < 2; ++b)
; #pragma unroll
;                 for (int m = 0; m < 4; ++m)
; #pragma unroll
;                     for (int n = 0; n < 2; ++n) acc[a][b][m][n] = (f32x4){0.f, 0.f, 0.f, 0.f};
.LBB0_261:
	s_ashr_i32 s19, s18, 31
	s_lshl_b64 s[20:21], s[18:19], 19
	s_add_u32 s20, s34, s20
	s_addc_u32 s21, s35, s21
	s_ashr_i32 s17, s16, 31
	s_lshl_b64 s[22:23], s[16:17], 19
	s_add_u32 s22, s36, s22
	v_mov_b32_e32 v123, 0
	s_addc_u32 s23, s37, s23
	s_and_b64 vcc, exec, s[2:3]
	s_cbranch_vccz .Lzskip_1
	v_mov_b32_e32 v122, v123
	v_mov_b32_e32 v121, v123
	v_mov_b32_e32 v120, v123
	v_mov_b32_e32 v119, v123
	v_mov_b32_e32 v118, v123
	v_mov_b32_e32 v117, v123
	v_mov_b32_e32 v116, v123
	v_mov_b32_e32 v111, v123
	v_mov_b32_e32 v110, v123
	v_mov_b32_e32 v109, v123
	v_mov_b32_e32 v108, v123
	v_mov_b32_e32 v103, v123
	v_mov_b32_e32 v102, v123
	v_mov_b32_e32 v101, v123
	v_mov_b32_e32 v100, v123
	v_mov_b32_e32 v95, v123
	v_mov_b32_e32 v94, v123
	v_mov_b32_e32 v93, v123
	v_mov_b32_e32 v92, v123
	v_mov_b32_e32 v87, v123
	v_mov_b32_e32 v86, v123
	v_mov_b32_e32 v85, v123
	v_mov_b32_e32 v84, v123
	v_mov_b32_e32 v79, v123
	v_mov_b32_e32 v78, v123
	v_mov_b32_e32 v77, v123
	v_mov_b32_e32 v76, v123
	v_mov_b32_e32 v71, v123
	v_mov_b32_e32 v70, v123
	v_mov_b32_e32 v69, v123
	v_mov_b32_e32 v68, v123
	v_mov_b32_e32 v127, v123
	v_mov_b32_e32 v126, v123
	v_mov_b32_e32 v125, v123
	v_mov_b32_e32 v124, v123
	v_mov_b32_e32 v115, v123
	v_mov_b32_e32 v114, v123
	v_mov_b32_e32 v113, v123
	v_mov_b32_e32 v112, v123
	v_mov_b32_e32 v107, v123
	v_mov_b32_e32 v106, v123
	v_mov_b32_e32 v105, v123
	v_mov_b32_e32 v104, v123
	v_mov_b32_e32 v99, v123
	v_mov_b32_e32 v98, v123
	v_mov_b32_e32 v97, v123
	v_mov_b32_e32 v96, v123
	v_mov_b32_e32 v91, v123
	v_mov_b32_e32 v90, v123
	v_mov_b32_e32 v89, v123
	v_mov_b32_e32 v88, v123
	v_mov_b32_e32 v83, v123
	v_mov_b32_e32 v82, v123
	v_mov_b32_e32 v81, v123
	v_mov_b32_e32 v80, v123
	v_mov_b32_e32 v75, v123
	v_mov_b32_e32 v74, v123
	v_mov_b32_e32 v73, v123
	v_mov_b32_e32 v72, v123
	v_mov_b32_e32 v67, v123
	v_mov_b32_e32 v66, v123
	v_mov_b32_e32 v65, v123
	v_mov_b32_e32 v64, v123
	v_mov_b32_e32 v63, v123
	v_mov_b32_e32 v62, v123
	v_mov_b32_e32 v61, v123
	v_mov_b32_e32 v60, v123
	v_mov_b32_e32 v55, v123
	v_mov_b32_e32 v54, v123
	v_mov_b32_e32 v53, v123
	v_mov_b32_e32 v52, v123
	v_mov_b32_e32 v47, v123
	v_mov_b32_e32 v46, v123
	v_mov_b32_e32 v45, v123
	v_mov_b32_e32 v44, v123
	v_mov_b32_e32 v39, v123
	v_mov_b32_e32 v38, v123
	v_mov_b32_e32 v37, v123
	v_mov_b32_e32 v36, v123
	v_mov_b32_e32 v31, v123
	v_mov_b32_e32 v30, v123
	v_mov_b32_e32 v29, v123
	v_mov_b32_e32 v28, v123
	v_mov_b32_e32 v23, v123
	v_mov_b32_e32 v22, v123
	v_mov_b32_e32 v21, v123
	v_mov_b32_e32 v20, v123
	v_mov_b32_e32 v15, v123
	v_mov_b32_e32 v14, v123
	v_mov_b32_e32 v13, v123
	v_mov_b32_e32 v12, v123
	v_mov_b32_e32 v7, v123
	v_mov_b32_e32 v6, v123
	v_mov_b32_e32 v5, v123
	v_mov_b32_e32 v4, v123
	v_mov_b32_e32 v59, v123
	v_mov_b32_e32 v58, v123
	v_mov_b32_e32 v57, v123
	v_mov_b32_e32 v56, v123
	v_mov_b32_e32 v51, v123
	v_mov_b32_e32 v50, v123
	v_mov_b32_e32 v49, v123
	v_mov_b32_e32 v48, v123
	v_mov_b32_e32 v43, v123
	v_mov_b32_e32 v42, v123
	v_mov_b32_e32 v41, v123
	v_mov_b32_e32 v40, v123
	v_mov_b32_e32 v35, v123
	v_mov_b32_e32 v34, v123
	v_mov_b32_e32 v33, v123
	v_mov_b32_e32 v32, v123
	v_mov_b32_e32 v27, v123
	v_mov_b32_e32 v26, v123
	v_mov_b32_e32 v25, v123
	v_mov_b32_e32 v24, v123
	v_mov_b32_e32 v19, v123
	v_mov_b32_e32 v18, v123
	v_mov_b32_e32 v17, v123
	v_mov_b32_e32 v16, v123
	v_mov_b32_e32 v11, v123
	v_mov_b32_e32 v10, v123
	v_mov_b32_e32 v9, v123
	v_mov_b32_e32 v8, v123
	v_mov_b32_e32 v3, v123
	v_mov_b32_e32 v2, v123
	v_mov_b32_e32 v1, v123
	v_mov_b32_e32 v0, v123
	s_cbranch_vccnz .LBB0_266
.Lzskip_1:
	s_and_b64 s[30:31], s[4:5], exec
	s_cselect_b32 s17, s21, s29
	s_cselect_b32 s19, s20, s28
	s_cselect_b32 s55, s23, s27
	s_cselect_b32 s56, s22, s26
	s_ashr_i32 s25, s24, 31
	s_lshl_b64 s[30:31], s[24:25], 14
	s_add_u32 s25, s26, 0x100
	s_addc_u32 s57, s27, 0
	v_lshl_add_u64 v[146:147], v[136:137], 0, s[30:31]
	s_add_u32 s26, s28, 0x40080
	v_mov_b32_e32 v0, 0
	v_lshl_add_u64 v[148:149], v[146:147], 0, s[14:15]
	s_addc_u32 s27, s29, 0
	s_mov_b32 s58, 0
	v_mov_b32_e32 v1, v0
	v_mov_b32_e32 v2, v0
	v_mov_b32_e32 v3, v0
	v_mov_b32_e32 v8, v0
	v_mov_b32_e32 v9, v0
	v_mov_b32_e32 v10, v0
	v_mov_b32_e32 v11, v0
	v_mov_b32_e32 v16, v0
	v_mov_b32_e32 v17, v0
	v_mov_b32_e32 v18, v0
	v_mov_b32_e32 v19, v0
	v_mov_b32_e32 v24, v0
	v_mov_b32_e32 v25, v0
	v_mov_b32_e32 v26, v0
	v_mov_b32_e32 v27, v0
	v_mov_b32_e32 v32, v0
	v_mov_b32_e32 v33, v0
	v_mov_b32_e32 v34, v0
	v_mov_b32_e32 v35, v0
	v_mov_b32_e32 v40, v0
	v_mov_b32_e32 v41, v0
	v_mov_b32_e32 v42, v0
	v_mov_b32_e32 v43, v0
	v_mov_b32_e32 v48, v0
	v_mov_b32_e32 v49, v0
	v_mov_b32_e32 v50, v0
	v_mov_b32_e32 v51, v0
	v_mov_b32_e32 v56, v0
	v_mov_b32_e32 v57, v0
	v_mov_b32_e32 v58, v0
	v_mov_b32_e32 v59, v0
	v_mov_b32_e32 v4, v0
	v_mov_b32_e32 v5, v0
	v_mov_b32_e32 v6, v0
	v_mov_b32_e32 v7, v0
	v_mov_b32_e32 v12, v0
	v_mov_b32_e32 v13, v0
	v_mov_b32_e32 v14, v0
	v_mov_b32_e32 v15, v0
	v_mov_b32_e32 v20, v0
	v_mov_b32_e32 v21, v0
	v_mov_b32_e32 v22, v0
	v_mov_b32_e32 v23, v0
	v_mov_b32_e32 v28, v0
	v_mov_b32_e32 v29, v0
	v_mov_b32_e32 v30, v0
	v_mov_b32_e32 v31, v0
	v_mov_b32_e32 v36, v0
	v_mov_b32_e32 v37, v0
	v_mov_b32_e32 v38, v0
	v_mov_b32_e32 v39, v0
	v_mov_b32_e32 v44, v0
	v_mov_b32_e32 v45, v0
	v_mov_b32_e32 v46, v0
	v_mov_b32_e32 v47, v0
	v_mov_b32_e32 v52, v0
	v_mov_b32_e32 v53, v0
	v_mov_b32_e32 v54, v0
	v_mov_b32_e32 v55, v0
	v_mov_b32_e32 v60, v0
	v_mov_b32_e32 v61, v0
	v_mov_b32_e32 v62, v0
	v_mov_b32_e32 v63, v0
	v_mov_b32_e32 v64, v0
	v_mov_b32_e32 v65, v0
	v_mov_b32_e32 v66, v0
	v_mov_b32_e32 v67, v0
	v_mov_b32_e32 v72, v0
	v_mov_b32_e32 v73, v0
	v_mov_b32_e32 v74, v0
	v_mov_b32_e32 v75, v0
	v_mov_b32_e32 v80, v0
	v_mov_b32_e32 v81, v0
	v_mov_b32_e32 v82, v0
	v_mov_b32_e32 v83, v0
	v_mov_b32_e32 v88, v0
	v_mov_b32_e32 v89, v0
	v_mov_b32_e32 v90, v0
	v_mov_b32_e32 v91, v0
	v_mov_b32_e32 v96, v0
	v_mov_b32_e32 v97, v0
	v_mov_b32_e32 v98, v0
	v_mov_b32_e32 v99, v0
	v_mov_b32_e32 v104, v0
	v_mov_b32_e32 v105, v0
	v_mov_b32_e32 v106, v0
	v_mov_b32_e32 v107, v0
	v_mov_b32_e32 v112, v0
	v_mov_b32_e32 v113, v0
	v_mov_b32_e32 v114, v0
	v_mov_b32_e32 v115, v0
	v_mov_b32_e32 v124, v0
	v_mov_b32_e32 v125, v0
	v_mov_b32_e32 v126, v0
	v_mov_b32_e32 v127, v0
	v_mov_b32_e32 v68, v0
	v_mov_b32_e32 v69, v0
	v_mov_b32_e32 v70, v0
	v_mov_b32_e32 v71, v0
	v_mov_b32_e32 v76, v0
	v_mov_b32_e32 v77, v0
	v_mov_b32_e32 v78, v0
	v_mov_b32_e32 v79, v0
	v_mov_b32_e32 v84, v0
	v_mov_b32_e32 v85, v0
	v_mov_b32_e32 v86, v0
	v_mov_b32_e32 v87, v0
	v_mov_b32_e32 v92, v0
	v_mov_b32_e32 v93, v0
	v_mov_b32_e32 v94, v0
	v_mov_b32_e32 v95, v0
	v_mov_b32_e32 v100, v0
	v_mov_b32_e32 v101, v0
	v_mov_b32_e32 v102, v0
	v_mov_b32_e32 v103, v0
	v_mov_b32_e32 v108, v0
	v_mov_b32_e32 v109, v0
	v_mov_b32_e32 v110, v0
	v_mov_b32_e32 v111, v0
	v_mov_b32_e32 v116, v0
	v_mov_b32_e32 v117, v0
	v_mov_b32_e32 v118, v0
	v_mov_b32_e32 v119, v0
	v_mov_b32_e32 v120, v0
	v_mov_b32_e32 v121, v0
	v_mov_b32_e32 v122, v0
	v_mov_b32_e32 v123, v0
	s_branch .LBB0_264

; template <class Epi>
; __device__ __forceinline__ void gemm_phase(LAS unsigned char* lds, const int tid, const Gemm g, const StaticOrder& S, const Epi& E) {
;     ...
;         const bool has_next = S.next(ui + 1, nxt);
;         const char* nA = has_next ? (const char*)g.A + (size_t)nxt.pm * tstepA + (size_t)(nxt.pn >> g.a_grp_shift) * g.a_grp_bytes : cA;
;         const char* nB = has_next ? (const char*)g.Bt + (size_t)nxt.pn * tstepB : cB;
;         for (int t = 0; t < nt; t += 2) {
;             const bool last = (t == nt - 2);
;             const char* a1 = cA + (size_t)(t + 1) * kstep;
;             const char* a2 = last ? nA : cA + (size_t)(t + 2) * kstep; const char* b2 = last ? nB : cB + (size_t)(t + 2) * kstep;
;             const char* a3 = a2 + kstep; const char* b3 = b2 + kstep;
;             if constexpr (Epi::SS_LDS) { if (last) {
;                 const char* sp = (const char*)E.ss + (size_t)cur.pm * (256 * 64) + (size_t)tid * 16;
;     ...
; #pragma unroll
;         for (int a = 0; a < 2; ++a)
; #pragma unroll
;             for (int b = 0; b < 2; ++b)
; #pragma unroll
;                 for (int m = 0; m < 4; ++m)
; #pragma unroll
;                     for (int n = 0; n < 2; ++n) acc[a][b][m][n] = (f32x4){0.f, 0.f, 0.f, 0.f};
.LBB0_440:
	s_ashr_i32 s27, s26, 31
	s_lshl_b64 s[28:29], s[26:27], 19
	s_add_u32 s28, s43, s28
	s_addc_u32 s29, s44, s29
	s_ashr_i32 s25, s24, 31
	s_lshl_b64 s[30:31], s[24:25], 19
	s_add_u32 s30, s45, s30
	v_mov_b32_e32 v127, 0
	s_addc_u32 s31, s46, s31
	s_andn2_b64 vcc, exec, s[18:19]
	s_cbranch_vccz .Lzskip_2
	v_mov_b32_e32 v126, v127
	v_mov_b32_e32 v125, v127
	v_mov_b32_e32 v124, v127
	v_mov_b32_e32 v123, v127
	v_mov_b32_e32 v122, v127
	v_mov_b32_e32 v121, v127
	v_mov_b32_e32 v120, v127
	v_mov_b32_e32 v111, v127
	v_mov_b32_e32 v110, v127
	v_mov_b32_e32 v109, v127
	v_mov_b32_e32 v108, v127
	v_mov_b32_e32 v107, v127
	v_mov_b32_e32 v106, v127
	v_mov_b32_e32 v105, v127
	v_mov_b32_e32 v104, v127
	v_mov_b32_e32 v95, v127
	v_mov_b32_e32 v94, v127
	v_mov_b32_e32 v93, v127
	v_mov_b32_e32 v92, v127
	v_mov_b32_e32 v91, v127
	v_mov_b32_e32 v90, v127
	v_mov_b32_e32 v89, v127
	v_mov_b32_e32 v88, v127
	v_mov_b32_e32 v79, v127
	v_mov_b32_e32 v78, v127
	v_mov_b32_e32 v77, v127
	v_mov_b32_e32 v76, v127
	v_mov_b32_e32 v75, v127
	v_mov_b32_e32 v74, v127
	v_mov_b32_e32 v73, v127
	v_mov_b32_e32 v72, v127
	v_mov_b32_e32 v119, v127
	v_mov_b32_e32 v118, v127
	v_mov_b32_e32 v117, v127
	v_mov_b32_e32 v116, v127
	v_mov_b32_e32 v115, v127
	v_mov_b32_e32 v114, v127
	v_mov_b32_e32 v113, v127
	v_mov_b32_e32 v112, v127
	v_mov_b32_e32 v103, v127
	v_mov_b32_e32 v102, v127
	v_mov_b32_e32 v101, v127
	v_mov_b32_e32 v100, v127
	v_mov_b32_e32 v99, v127
	v_mov_b32_e32 v98, v127
	v_mov_b32_e32 v97, v127
	v_mov_b32_e32 v96, v127
	v_mov_b32_e32 v87, v127
	v_mov_b32_e32 v86, v127
	v_mov_b32_e32 v85, v127
	v_mov_b32_e32 v84, v127
	v_mov_b32_e32 v83, v127
	v_mov_b32_e32 v82, v127
	v_mov_b32_e32 v81, v127
	v_mov_b32_e32 v80, v127
	v_mov_b32_e32 v71, v127
	v_mov_b32_e32 v70, v127
	v_mov_b32_e32 v69, v127
	v_mov_b32_e32 v68, v127
	v_mov_b32_e32 v67, v127
	v_mov_b32_e32 v66, v127
	v_mov_b32_e32 v65, v127
	v_mov_b32_e32 v64, v127
	v_mov_b32_e32 v63, v127
	v_mov_b32_e32 v62, v127
	v_mov_b32_e32 v61, v127
	v_mov_b32_e32 v60, v127
	v_mov_b32_e32 v59, v127
	v_mov_b32_e32 v58, v127
	v_mov_b32_e32 v57, v127
	v_mov_b32_e32 v56, v127
	v_mov_b32_e32 v47, v127
	v_mov_b32_e32 v46, v127
	v_mov_b32_e32 v45, v127
	v_mov_b32_e32 v44, v127
	v_mov_b32_e32 v43, v127
	v_mov_b32_e32 v42, v127
	v_mov_b32_e32 v41, v127
	v_mov_b32_e32 v40, v127
	v_mov_b32_e32 v31, v127
	v_mov_b32_e32 v30, v127
	v_mov_b32_e32 v29, v127
	v_mov_b32_e32 v28, v127
	v_mov_b32_e32 v27, v127
	v_mov_b32_e32 v26, v127
	v_mov_b32_e32 v25, v127
	v_mov_b32_e32 v24, v127
	v_mov_b32_e32 v15, v127
	v_mov_b32_e32 v14, v127
	v_mov_b32_e32 v13, v127
	v_mov_b32_e32 v12, v127
	v_mov_b32_e32 v11, v127
	v_mov_b32_e32 v10, v127
	v_mov_b32_e32 v9, v127
	v_mov_b32_e32 v8, v127
	v_mov_b32_e32 v55, v127
	v_mov_b32_e32 v54, v127
	v_mov_b32_e32 v53, v127
	v_mov_b32_e32 v52, v127
	v_mov_b32_e32 v51, v127
	v_mov_b32_e32 v50, v127
	v_mov_b32_e32 v49, v127
	v_mov_b32_e32 v48, v127
	v_mov_b32_e32 v39, v127
	v_mov_b32_e32 v38, v127
	v_mov_b32_e32 v37, v127
	v_mov_b32_e32 v36, v127
	v_mov_b32_e32 v35, v127
	v_mov_b32_e32 v34, v127
	v_mov_b32_e32 v33, v127
	v_mov_b32_e32 v32, v127
	v_mov_b32_e32 v23, v127
	v_mov_b32_e32 v22, v127
	v_mov_b32_e32 v21, v127
	v_mov_b32_e32 v20, v127
	v_mov_b32_e32 v19, v127
	v_mov_b32_e32 v18, v127
	v_mov_b32_e32 v17, v127
	v_mov_b32_e32 v16, v127
	v_mov_b32_e32 v7, v127
	v_mov_b32_e32 v6, v127
	v_mov_b32_e32 v5, v127
	v_mov_b32_e32 v4, v127
	v_mov_b32_e32 v3, v127
	v_mov_b32_e32 v2, v127
	v_mov_b32_e32 v1, v127
	v_mov_b32_e32 v0, v127
	s_cbranch_vccnz .LBB0_445
.Lzskip_2:
	s_and_b64 s[40:41], s[2:3], exec
	s_cselect_b32 s4, s29, s39
	s_cselect_b32 s25, s28, s38
	s_cselect_b32 s27, s31, s37
	s_cselect_b32 s66, s30, s36
	s_ashr_i32 s35, s34, 31
	s_lshl_b64 s[40:41], s[34:35], 14
	s_add_u32 s35, s36, 0x100
	s_addc_u32 s67, s37, 0
	v_lshl_add_u64 v[150:151], v[140:141], 0, s[40:41]
	s_add_u32 s36, s38, 0x40080
	v_mov_b32_e32 v0, 0
	v_lshl_add_u64 v[152:153], v[150:151], 0, s[22:23]
	s_addc_u32 s37, s39, 0
	s_mov_b32 s68, 0
	v_mov_b32_e32 v1, v0
	v_mov_b32_e32 v2, v0
	v_mov_b32_e32 v3, v0
	v_mov_b32_e32 v4, v0
	v_mov_b32_e32 v5, v0
	v_mov_b32_e32 v6, v0
	v_mov_b32_e32 v7, v0
	v_mov_b32_e32 v16, v0
	v_mov_b32_e32 v17, v0
	v_mov_b32_e32 v18, v0
	v_mov_b32_e32 v19, v0
	v_mov_b32_e32 v20, v0
	v_mov_b32_e32 v21, v0
	v_mov_b32_e32 v22, v0
	v_mov_b32_e32 v23, v0
	v_mov_b32_e32 v32, v0
	v_mov_b32_e32 v33, v0
	v_mov_b32_e32 v34, v0
	v_mov_b32_e32 v35, v0
	v_mov_b32_e32 v36, v0
	v_mov_b32_e32 v37, v0
	v_mov_b32_e32 v38, v0
	v_mov_b32_e32 v39, v0
	v_mov_b32_e32 v48, v0
	v_mov_b32_e32 v49, v0
	v_mov_b32_e32 v50, v0
	v_mov_b32_e32 v51, v0
	v_mov_b32_e32 v52, v0
	v_mov_b32_e32 v53, v0
	v_mov_b32_e32 v54, v0
	v_mov_b32_e32 v55, v0
	v_mov_b32_e32 v8, v0
	v_mov_b32_e32 v9, v0
	v_mov_b32_e32 v10, v0
	v_mov_b32_e32 v11, v0
	v_mov_b32_e32 v12, v0
	v_mov_b32_e32 v13, v0
	v_mov_b32_e32 v14, v0
	v_mov_b32_e32 v15, v0
	v_mov_b32_e32 v24, v0
	v_mov_b32_e32 v25, v0
	v_mov_b32_e32 v26, v0
	v_mov_b32_e32 v27, v0
	v_mov_b32_e32 v28, v0
	v_mov_b32_e32 v29, v0
	v_mov_b32_e32 v30, v0
	v_mov_b32_e32 v31, v0
	v_mov_b32_e32 v40, v0
	v_mov_b32_e32 v41, v0
	v_mov_b32_e32 v42, v0
	v_mov_b32_e32 v43, v0
	v_mov_b32_e32 v44, v0
	v_mov_b32_e32 v45, v0
	v_mov_b32_e32 v46, v0
	v_mov_b32_e32 v47, v0
	v_mov_b32_e32 v56, v0
	v_mov_b32_e32 v57, v0
	v_mov_b32_e32 v58, v0
	v_mov_b32_e32 v59, v0
	v_mov_b32_e32 v60, v0
	v_mov_b32_e32 v61, v0
	v_mov_b32_e32 v62, v0
	v_mov_b32_e32 v63, v0
	v_mov_b32_e32 v64, v0
	v_mov_b32_e32 v65, v0
	v_mov_b32_e32 v66, v0
	v_mov_b32_e32 v67, v0
	v_mov_b32_e32 v68, v0
	v_mov_b32_e32 v69, v0
	v_mov_b32_e32 v70, v0
	v_mov_b32_e32 v71, v0
	v_mov_b32_e32 v80, v0
	v_mov_b32_e32 v81, v0
	v_mov_b32_e32 v82, v0
	v_mov_b32_e32 v83, v0
	v_mov_b32_e32 v84, v0
	v_mov_b32_e32 v85, v0
	v_mov_b32_e32 v86, v0
	v_mov_b32_e32 v87, v0
	v_mov_b32_e32 v96, v0
	v_mov_b32_e32 v97, v0
	v_mov_b32_e32 v98, v0
	v_mov_b32_e32 v99, v0
	v_mov_b32_e32 v100, v0
	v_mov_b32_e32 v101, v0
	v_mov_b32_e32 v102, v0
	v_mov_b32_e32 v103, v0
	v_mov_b32_e32 v112, v0
	v_mov_b32_e32 v113, v0
	v_mov_b32_e32 v114, v0
	v_mov_b32_e32 v115, v0
	v_mov_b32_e32 v116, v0
	v_mov_b32_e32 v117, v0
	v_mov_b32_e32 v118, v0
	v_mov_b32_e32 v119, v0
	v_mov_b32_e32 v72, v0
	v_mov_b32_e32 v73, v0
	v_mov_b32_e32 v74, v0
	v_mov_b32_e32 v75, v0
	v_mov_b32_e32 v76, v0
	v_mov_b32_e32 v77, v0
	v_mov_b32_e32 v78, v0
	v_mov_b32_e32 v79, v0
	v_mov_b32_e32 v88, v0
	v_mov_b32_e32 v89, v0
	v_mov_b32_e32 v90, v0
	v_mov_b32_e32 v91, v0
	v_mov_b32_e32 v92, v0
	v_mov_b32_e32 v93, v0
	v_mov_b32_e32 v94, v0
	v_mov_b32_e32 v95, v0
	v_mov_b32_e32 v104, v0
	v_mov_b32_e32 v105, v0
	v_mov_b32_e32 v106, v0
	v_mov_b32_e32 v107, v0
	v_mov_b32_e32 v108, v0
	v_mov_b32_e32 v109, v0
	v_mov_b32_e32 v110, v0
	v_mov_b32_e32 v111, v0
	v_mov_b32_e32 v120, v0
	v_mov_b32_e32 v121, v0
	v_mov_b32_e32 v122, v0
	v_mov_b32_e32 v123, v0
	v_mov_b32_e32 v124, v0
	v_mov_b32_e32 v125, v0
	v_mov_b32_e32 v126, v0
	v_mov_b32_e32 v127, v0
	s_branch .LBB0_443

; template <class Epi>
; __device__ __forceinline__ void gemm_phase(LAS unsigned char* lds, const int tid, const Gemm g, const StaticOrder& S, const Epi& E) {
;     ...
;         const bool has_next = S.next(ui + 1, nxt);
;         const char* nA = has_next ? (const char*)g.A + (size_t)nxt.pm * tstepA + (size_t)(nxt.pn >> g.a_grp_shift) * g.a_grp_bytes : cA;
;         const char* nB = has_next ? (const char*)g.Bt + (size_t)nxt.pn * tstepB : cB;
;         for (int t = 0; t < nt; t += 2) {
;             const bool last = (t == nt - 2);
;             const char* a1 = cA + (size_t)(t + 1) * kstep;
;             const char* a2 = last ? nA : cA + (size_t)(t + 2) * kstep; const char* b2 = last ? nB : cB + (size_t)(t + 2) * kstep;
;             const char* a3 = a2 + kstep; const char* b3 = b2 + kstep;
;             if constexpr (Epi::SS_LDS) { if (last) {
;                 const char* sp = (const char*)E.ss + (size_t)cur.pm * (256 * 64) + (size_t)tid * 16;
;     ...
; #pragma unroll
;         for (int a = 0; a < 2; ++a)
; #pragma unroll
;             for (int b = 0; b < 2; ++b)
; #pragma unroll
;                 for (int m = 0; m < 4; ++m)
; #pragma unroll
;                     for (int n = 0; n < 2; ++n) acc[a][b][m][n] = (f32x4){0.f, 0.f, 0.f, 0.f};
.LBB0_726:
	s_ashr_i32 s23, s22, 31
	s_lshl_b64 s[24:25], s[22:23], 19
	s_add_u32 s24, s38, s24
	s_addc_u32 s25, s39, s25
	s_ashr_i32 s21, s20, 31
	s_lshl_b64 s[26:27], s[20:21], 19
	s_add_u32 s26, s40, s26
	v_mov_b32_e32 v123, 0
	s_addc_u32 s27, s41, s27
	s_andn2_b64 vcc, exec, s[16:17]
	s_cbranch_vccz .Lzskip_3
	v_mov_b32_e32 v122, v123
	v_mov_b32_e32 v121, v123
	v_mov_b32_e32 v120, v123
	v_mov_b32_e32 v127, v123
	v_mov_b32_e32 v126, v123
	v_mov_b32_e32 v125, v123
	v_mov_b32_e32 v124, v123
	v_mov_b32_e32 v111, v123
	v_mov_b32_e32 v110, v123
	v_mov_b32_e32 v109, v123
	v_mov_b32_e32 v108, v123
	v_mov_b32_e32 v107, v123
	v_mov_b32_e32 v106, v123
	v_mov_b32_e32 v105, v123
	v_mov_b32_e32 v104, v123
	v_mov_b32_e32 v95, v123
	v_mov_b32_e32 v94, v123
	v_mov_b32_e32 v93, v123
	v_mov_b32_e32 v92, v123
	v_mov_b32_e32 v91, v123
	v_mov_b32_e32 v90, v123
	v_mov_b32_e32 v89, v123
	v_mov_b32_e32 v88, v123
	v_mov_b32_e32 v79, v123
	v_mov_b32_e32 v78, v123
	v_mov_b32_e32 v77, v123
	v_mov_b32_e32 v76, v123
	v_mov_b32_e32 v75, v123
	v_mov_b32_e32 v74, v123
	v_mov_b32_e32 v73, v123
	v_mov_b32_e32 v72, v123
	v_mov_b32_e32 v119, v123
	v_mov_b32_e32 v118, v123
	v_mov_b32_e32 v117, v123
	v_mov_b32_e32 v116, v123
	v_mov_b32_e32 v115, v123
	v_mov_b32_e32 v114, v123
	v_mov_b32_e32 v113, v123
	v_mov_b32_e32 v112, v123
	v_mov_b32_e32 v103, v123
	v_mov_b32_e32 v102, v123
	v_mov_b32_e32 v101, v123
	v_mov_b32_e32 v100, v123
	v_mov_b32_e32 v99, v123
	v_mov_b32_e32 v98, v123
	v_mov_b32_e32 v97, v123
	v_mov_b32_e32 v96, v123
	v_mov_b32_e32 v87, v123
	v_mov_b32_e32 v86, v123
	v_mov_b32_e32 v85, v123
	v_mov_b32_e32 v84, v123
	v_mov_b32_e32 v83, v123
	v_mov_b32_e32 v82, v123
	v_mov_b32_e32 v81, v123
	v_mov_b32_e32 v80, v123
	v_mov_b32_e32 v71, v123
	v_mov_b32_e32 v70, v123
	v_mov_b32_e32 v69, v123
	v_mov_b32_e32 v68, v123
	v_mov_b32_e32 v67, v123
	v_mov_b32_e32 v66, v123
	v_mov_b32_e32 v65, v123
	v_mov_b32_e32 v64, v123
	v_mov_b32_e32 v63, v123
	v_mov_b32_e32 v62, v123
	v_mov_b32_e32 v61, v123
	v_mov_b32_e32 v60, v123
	v_mov_b32_e32 v59, v123
	v_mov_b32_e32 v58, v123
	v_mov_b32_e32 v57, v123
	v_mov_b32_e32 v56, v123
	v_mov_b32_e32 v47, v123
	v_mov_b32_e32 v46, v123
	v_mov_b32_e32 v45, v123
	v_mov_b32_e32 v44, v123
	v_mov_b32_e32 v43, v123
	v_mov_b32_e32 v42, v123
	v_mov_b32_e32 v41, v123
	v_mov_b32_e32 v40, v123
	v_mov_b32_e32 v31, v123
	v_mov_b32_e32 v30, v123
	v_mov_b32_e32 v29, v123
	v_mov_b32_e32 v28, v123
	v_mov_b32_e32 v27, v123
	v_mov_b32_e32 v26, v123
	v_mov_b32_e32 v25, v123
	v_mov_b32_e32 v24, v123
	v_mov_b32_e32 v15, v123
	v_mov_b32_e32 v14, v123
	v_mov_b32_e32 v13, v123
	v_mov_b32_e32 v12, v123
	v_mov_b32_e32 v11, v123
	v_mov_b32_e32 v10, v123
	v_mov_b32_e32 v9, v123
	v_mov_b32_e32 v8, v123
	v_mov_b32_e32 v55, v123
	v_mov_b32_e32 v54, v123
	v_mov_b32_e32 v53, v123
	v_mov_b32_e32 v52, v123
	v_mov_b32_e32 v51, v123
	v_mov_b32_e32 v50, v123
	v_mov_b32_e32 v49, v123
	v_mov_b32_e32 v48, v123
	v_mov_b32_e32 v39, v123
	v_mov_b32_e32 v38, v123
	v_mov_b32_e32 v37, v123
	v_mov_b32_e32 v36, v123
	v_mov_b32_e32 v35, v123
	v_mov_b32_e32 v34, v123
	v_mov_b32_e32 v33, v123
	v_mov_b32_e32 v32, v123
	v_mov_b32_e32 v23, v123
	v_mov_b32_e32 v22, v123
	v_mov_b32_e32 v21, v123
	v_mov_b32_e32 v20, v123
	v_mov_b32_e32 v19, v123
	v_mov_b32_e32 v18, v123
	v_mov_b32_e32 v17, v123
	v_mov_b32_e32 v16, v123
	v_mov_b32_e32 v7, v123
	v_mov_b32_e32 v6, v123
	v_mov_b32_e32 v5, v123
	v_mov_b32_e32 v4, v123
	v_mov_b32_e32 v3, v123
	v_mov_b32_e32 v2, v123
	v_mov_b32_e32 v1, v123
	v_mov_b32_e32 v0, v123
	s_cbranch_vccnz .LBB0_729
.Lzskip_3:
	s_and_b64 s[36:37], s[4:5], exec
	s_cselect_b32 s21, s25, s35
	s_cselect_b32 s23, s24, s34
	s_cselect_b32 s29, s27, s31
	s_cselect_b32 s57, s26, s30
	s_add_u32 s58, s30, 0x100
	s_addc_u32 s59, s31, 0
	s_add_u32 s30, s34, 0x40080
	v_mov_b32_e32 v0, 0
	s_addc_u32 s31, s35, 0
	s_mov_b32 s34, 0
	v_mov_b32_e32 v1, v0
	v_mov_b32_e32 v2, v0
	v_mov_b32_e32 v3, v0
	v_mov_b32_e32 v4, v0
	v_mov_b32_e32 v5, v0
	v_mov_b32_e32 v6, v0
	v_mov_b32_e32 v7, v0
	v_mov_b32_e32 v16, v0
	v_mov_b32_e32 v17, v0
	v_mov_b32_e32 v18, v0
	v_mov_b32_e32 v19, v0
	v_mov_b32_e32 v20, v0
	v_mov_b32_e32 v21, v0
	v_mov_b32_e32 v22, v0
	v_mov_b32_e32 v23, v0
	v_mov_b32_e32 v32, v0
	v_mov_b32_e32 v33, v0
	v_mov_b32_e32 v34, v0
	v_mov_b32_e32 v35, v0
	v_mov_b32_e32 v36, v0
	v_mov_b32_e32 v37, v0
	v_mov_b32_e32 v38, v0
	v_mov_b32_e32 v39, v0
	v_mov_b32_e32 v48, v0
	v_mov_b32_e32 v49, v0
	v_mov_b32_e32 v50, v0
	v_mov_b32_e32 v51, v0
	v_mov_b32_e32 v52, v0
	v_mov_b32_e32 v53, v0
	v_mov_b32_e32 v54, v0
	v_mov_b32_e32 v55, v0
	v_mov_b32_e32 v8, v0
	v_mov_b32_e32 v9, v0
	v_mov_b32_e32 v10, v0
	v_mov_b32_e32 v11, v0
	v_mov_b32_e32 v12, v0
	v_mov_b32_e32 v13, v0
	v_mov_b32_e32 v14, v0
	v_mov_b32_e32 v15, v0
	v_mov_b32_e32 v24, v0
	v_mov_b32_e32 v25, v0
	v_mov_b32_e32 v26, v0
	v_mov_b32_e32 v27, v0
	v_mov_b32_e32 v28, v0
	v_mov_b32_e32 v29, v0
	v_mov_b32_e32 v30, v0
	v_mov_b32_e32 v31, v0
	v_mov_b32_e32 v40, v0
	v_mov_b32_e32 v41, v0
	v_mov_b32_e32 v42, v0
	v_mov_b32_e32 v43, v0
	v_mov_b32_e32 v44, v0
	v_mov_b32_e32 v45, v0
	v_mov_b32_e32 v46, v0
	v_mov_b32_e32 v47, v0
	v_mov_b32_e32 v56, v0
	v_mov_b32_e32 v57, v0
	v_mov_b32_e32 v58, v0
	v_mov_b32_e32 v59, v0
	v_mov_b32_e32 v60, v0
	v_mov_b32_e32 v61, v0
	v_mov_b32_e32 v62, v0
	v_mov_b32_e32 v63, v0
	v_mov_b32_e32 v64, v0
	v_mov_b32_e32 v65, v0
	v_mov_b32_e32 v66, v0
	v_mov_b32_e32 v67, v0
	v_mov_b32_e32 v68, v0
	v_mov_b32_e32 v69, v0
	v_mov_b32_e32 v70, v0
	v_mov_b32_e32 v71, v0
	v_mov_b32_e32 v80, v0
	v_mov_b32_e32 v81, v0
	v_mov_b32_e32 v82, v0
	v_mov_b32_e32 v83, v0
	v_mov_b32_e32 v84, v0
	v_mov_b32_e32 v85, v0
	v_mov_b32_e32 v86, v0
	v_mov_b32_e32 v87, v0
	v_mov_b32_e32 v96, v0
	v_mov_b32_e32 v97, v0
	v_mov_b32_e32 v98, v0
	v_mov_b32_e32 v99, v0
	v_mov_b32_e32 v100, v0
	v_mov_b32_e32 v101, v0
	v_mov_b32_e32 v102, v0
	v_mov_b32_e32 v103, v0
	v_mov_b32_e32 v112, v0
	v_mov_b32_e32 v113, v0
	v_mov_b32_e32 v114, v0
	v_mov_b32_e32 v115, v0
	v_mov_b32_e32 v116, v0
	v_mov_b32_e32 v117, v0
	v_mov_b32_e32 v118, v0
	v_mov_b32_e32 v119, v0
	v_mov_b32_e32 v72, v0
	v_mov_b32_e32 v73, v0
	v_mov_b32_e32 v74, v0
	v_mov_b32_e32 v75, v0
	v_mov_b32_e32 v76, v0
	v_mov_b32_e32 v77, v0
	v_mov_b32_e32 v78, v0
	v_mov_b32_e32 v79, v0
	v_mov_b32_e32 v88, v0
	v_mov_b32_e32 v89, v0
	v_mov_b32_e32 v90, v0
	v_mov_b32_e32 v91, v0
	v_mov_b32_e32 v92, v0
	v_mov_b32_e32 v93, v0
	v_mov_b32_e32 v94, v0
	v_mov_b32_e32 v95, v0
	v_mov_b32_e32 v104, v0
	v_mov_b32_e32 v105, v0
	v_mov_b32_e32 v106, v0
	v_mov_b32_e32 v107, v0
	v_mov_b32_e32 v108, v0
	v_mov_b32_e32 v109, v0
	v_mov_b32_e32 v110, v0
	v_mov_b32_e32 v111, v0
	v_mov_b32_e32 v124, v0
	v_mov_b32_e32 v125, v0
	v_mov_b32_e32 v126, v0
	v_mov_b32_e32 v127, v0
	v_mov_b32_e32 v120, v0
	v_mov_b32_e32 v121, v0
	v_mov_b32_e32 v122, v0
	v_mov_b32_e32 v123, v0

; template <class Epi>
; __device__ __forceinline__ void gemm_phase(LAS unsigned char* lds, const int tid, const Gemm g, const StaticOrder& S, const Epi& E) {
;     ...
;         const bool has_next = S.next(ui + 1, nxt);
;         const char* nA = has_next ? (const char*)g.A + (size_t)nxt.pm * tstepA + (size_t)(nxt.pn >> g.a_grp_shift) * g.a_grp_bytes : cA;
;         const char* nB = has_next ? (const char*)g.Bt + (size_t)nxt.pn * tstepB : cB;
;         for (int t = 0; t < nt; t += 2) {
;             const bool last = (t == nt - 2);
;             const char* a1 = cA + (size_t)(t + 1) * kstep;
;             const char* a2 = last ? nA : cA + (size_t)(t + 2) * kstep; const char* b2 = last ? nB : cB + (size_t)(t + 2) * kstep;
;             const char* a3 = a2 + kstep; const char* b3 = b2 + kstep;
;             if constexpr (Epi::SS_LDS) { if (last) {
;                 const char* sp = (const char*)E.ss + (size_t)cur.pm * (256 * 64) + (size_t)tid * 16;
;     ...
; #pragma unroll
;         for (int a = 0; a < 2; ++a)
; #pragma unroll
;             for (int b = 0; b < 2; ++b)
; #pragma unroll
;                 for (int m = 0; m < 4; ++m)
; #pragma unroll
;                     for (int n = 0; n < 2; ++n) acc[a][b][m][n] = (f32x4){0.f, 0.f, 0.f, 0.f};
.LBB0_947:
	s_ashr_i32 s21, s20, 31
	s_lshl_b64 s[22:23], s[20:21], 17
	s_add_u32 s22, s35, s22
	s_addc_u32 s23, s36, s23
	s_ashr_i32 s19, s18, 31
	s_lshl_b64 s[24:25], s[18:19], 17
	s_add_u32 s24, s37, s24
	v_mov_b32_e32 v123, 0
	s_addc_u32 s25, s38, s25
	s_andn2_b64 vcc, exec, s[12:13]
	s_cbranch_vccz .Lzskip_5
	v_mov_b32_e32 v122, v123
	v_mov_b32_e32 v121, v123
	v_mov_b32_e32 v120, v123
	v_mov_b32_e32 v127, v123
	v_mov_b32_e32 v126, v123
	v_mov_b32_e32 v125, v123
	v_mov_b32_e32 v124, v123
	v_mov_b32_e32 v111, v123
	v_mov_b32_e32 v110, v123
	v_mov_b32_e32 v109, v123
	v_mov_b32_e32 v108, v123
	v_mov_b32_e32 v107, v123
	v_mov_b32_e32 v106, v123
	v_mov_b32_e32 v105, v123
	v_mov_b32_e32 v104, v123
	v_mov_b32_e32 v95, v123
	v_mov_b32_e32 v94, v123
	v_mov_b32_e32 v93, v123
	v_mov_b32_e32 v92, v123
	v_mov_b32_e32 v91, v123
	v_mov_b32_e32 v90, v123
	v_mov_b32_e32 v89, v123
	v_mov_b32_e32 v88, v123
	v_mov_b32_e32 v79, v123
	v_mov_b32_e32 v78, v123
	v_mov_b32_e32 v77, v123
	v_mov_b32_e32 v76, v123
	v_mov_b32_e32 v75, v123
	v_mov_b32_e32 v74, v123
	v_mov_b32_e32 v73, v123
	v_mov_b32_e32 v72, v123
	v_mov_b32_e32 v119, v123
	v_mov_b32_e32 v118, v123
	v_mov_b32_e32 v117, v123
	v_mov_b32_e32 v116, v123
	v_mov_b32_e32 v115, v123
	v_mov_b32_e32 v114, v123
	v_mov_b32_e32 v113, v123
	v_mov_b32_e32 v112, v123
	v_mov_b32_e32 v103, v123
	v_mov_b32_e32 v102, v123
	v_mov_b32_e32 v101, v123
	v_mov_b32_e32 v100, v123
	v_mov_b32_e32 v99, v123
	v_mov_b32_e32 v98, v123
	v_mov_b32_e32 v97, v123
	v_mov_b32_e32 v96, v123
	v_mov_b32_e32 v87, v123
	v_mov_b32_e32 v86, v123
	v_mov_b32_e32 v85, v123
	v_mov_b32_e32 v84, v123
	v_mov_b32_e32 v83, v123
	v_mov_b32_e32 v82, v123
	v_mov_b32_e32 v81, v123
	v_mov_b32_e32 v80, v123
	v_mov_b32_e32 v71, v123
	v_mov_b32_e32 v70, v123
	v_mov_b32_e32 v69, v123
	v_mov_b32_e32 v68, v123
	v_mov_b32_e32 v67, v123
	v_mov_b32_e32 v66, v123
	v_mov_b32_e32 v65, v123
	v_mov_b32_e32 v64, v123
	v_mov_b32_e32 v63, v123
	v_mov_b32_e32 v62, v123
	v_mov_b32_e32 v61, v123
	v_mov_b32_e32 v60, v123
	v_mov_b32_e32 v59, v123
	v_mov_b32_e32 v58, v123
	v_mov_b32_e32 v57, v123
	v_mov_b32_e32 v56, v123
	v_mov_b32_e32 v47, v123
	v_mov_b32_e32 v46, v123
	v_mov_b32_e32 v45, v123
	v_mov_b32_e32 v44, v123
	v_mov_b32_e32 v43, v123
	v_mov_b32_e32 v42, v123
	v_mov_b32_e32 v41, v123
	v_mov_b32_e32 v40, v123
	v_mov_b32_e32 v31, v123
	v_mov_b32_e32 v30, v123
	v_mov_b32_e32 v29, v123
	v_mov_b32_e32 v28, v123
	v_mov_b32_e32 v27, v123
	v_mov_b32_e32 v26, v123
	v_mov_b32_e32 v25, v123
	v_mov_b32_e32 v24, v123
	v_mov_b32_e32 v15, v123
	v_mov_b32_e32 v14, v123
	v_mov_b32_e32 v13, v123
	v_mov_b32_e32 v12, v123
	v_mov_b32_e32 v11, v123
	v_mov_b32_e32 v10, v123
	v_mov_b32_e32 v9, v123
	v_mov_b32_e32 v8, v123
	v_mov_b32_e32 v55, v123
	v_mov_b32_e32 v54, v123
	v_mov_b32_e32 v53, v123
	v_mov_b32_e32 v52, v123
	v_mov_b32_e32 v51, v123
	v_mov_b32_e32 v50, v123
	v_mov_b32_e32 v49, v123
	v_mov_b32_e32 v48, v123
	v_mov_b32_e32 v39, v123
	v_mov_b32_e32 v38, v123
	v_mov_b32_e32 v37, v123
	v_mov_b32_e32 v36, v123
	v_mov_b32_e32 v35, v123
	v_mov_b32_e32 v34, v123
	v_mov_b32_e32 v33, v123
	v_mov_b32_e32 v32, v123
	v_mov_b32_e32 v23, v123
	v_mov_b32_e32 v22, v123
	v_mov_b32_e32 v21, v123
	v_mov_b32_e32 v20, v123
	v_mov_b32_e32 v19, v123
	v_mov_b32_e32 v18, v123
	v_mov_b32_e32 v17, v123
	v_mov_b32_e32 v16, v123
	v_mov_b32_e32 v7, v123
	v_mov_b32_e32 v6, v123
	v_mov_b32_e32 v5, v123
	v_mov_b32_e32 v4, v123
	v_mov_b32_e32 v3, v123
	v_mov_b32_e32 v2, v123
	v_mov_b32_e32 v1, v123
	v_mov_b32_e32 v0, v123
	s_cbranch_vccnz .LBB0_950
.Lzskip_5:
	s_and_b64 s[30:31], s[2:3], exec
	s_cselect_b32 s19, s23, s29
	s_cselect_b32 s21, s22, s28
	s_cselect_b32 s52, s25, s27
	s_cselect_b32 s53, s24, s26
	s_add_u32 s54, s26, 0x100
	s_addc_u32 s55, s27, 0
	s_add_u32 s26, s28, 0x10080
	v_mov_b32_e32 v0, 0
	s_addc_u32 s27, s29, 0
	s_mov_b32 s28, 0
	v_mov_b32_e32 v1, v0
	v_mov_b32_e32 v2, v0
	v_mov_b32_e32 v3, v0
	v_mov_b32_e32 v4, v0
	v_mov_b32_e32 v5, v0
	v_mov_b32_e32 v6, v0
	v_mov_b32_e32 v7, v0
	v_mov_b32_e32 v16, v0
	v_mov_b32_e32 v17, v0
	v_mov_b32_e32 v18, v0
	v_mov_b32_e32 v19, v0
	v_mov_b32_e32 v20, v0
	v_mov_b32_e32 v21, v0
	v_mov_b32_e32 v22, v0
	v_mov_b32_e32 v23, v0
	v_mov_b32_e32 v32, v0
	v_mov_b32_e32 v33, v0
	v_mov_b32_e32 v34, v0
	v_mov_b32_e32 v35, v0
	v_mov_b32_e32 v36, v0
	v_mov_b32_e32 v37, v0
	v_mov_b32_e32 v38, v0
	v_mov_b32_e32 v39, v0
	v_mov_b32_e32 v48, v0
	v_mov_b32_e32 v49, v0
	v_mov_b32_e32 v50, v0
	v_mov_b32_e32 v51, v0
	v_mov_b32_e32 v52, v0
	v_mov_b32_e32 v53, v0
	v_mov_b32_e32 v54, v0
	v_mov_b32_e32 v55, v0
	v_mov_b32_e32 v8, v0
	v_mov_b32_e32 v9, v0
	v_mov_b32_e32 v10, v0
	v_mov_b32_e32 v11, v0
	v_mov_b32_e32 v12, v0
	v_mov_b32_e32 v13, v0
	v_mov_b32_e32 v14, v0
	v_mov_b32_e32 v15, v0
	v_mov_b32_e32 v24, v0
	v_mov_b32_e32 v25, v0
	v_mov_b32_e32 v26, v0
	v_mov_b32_e32 v27, v0
	v_mov_b32_e32 v28, v0
	v_mov_b32_e32 v29, v0
	v_mov_b32_e32 v30, v0
	v_mov_b32_e32 v31, v0
	v_mov_b32_e32 v40, v0
	v_mov_b32_e32 v41, v0
	v_mov_b32_e32 v42, v0
	v_mov_b32_e32 v43, v0
	v_mov_b32_e32 v44, v0
	v_mov_b32_e32 v45, v0
	v_mov_b32_e32 v46, v0
	v_mov_b32_e32 v47, v0
	v_mov_b32_e32 v56, v0
	v_mov_b32_e32 v57, v0
	v_mov_b32_e32 v58, v0
	v_mov_b32_e32 v59, v0
	v_mov_b32_e32 v60, v0
	v_mov_b32_e32 v61, v0
	v_mov_b32_e32 v62, v0
	v_mov_b32_e32 v63, v0
	v_mov_b32_e32 v64, v0
	v_mov_b32_e32 v65, v0
	v_mov_b32_e32 v66, v0
	v_mov_b32_e32 v67, v0
	v_mov_b32_e32 v68, v0
	v_mov_b32_e32 v69, v0
	v_mov_b32_e32 v70, v0
	v_mov_b32_e32 v71, v0
	v_mov_b32_e32 v80, v0
	v_mov_b32_e32 v81, v0
	v_mov_b32_e32 v82, v0
	v_mov_b32_e32 v83, v0
	v_mov_b32_e32 v84, v0
	v_mov_b32_e32 v85, v0
	v_mov_b32_e32 v86, v0
	v_mov_b32_e32 v87, v0
	v_mov_b32_e32 v96, v0
	v_mov_b32_e32 v97, v0
	v_mov_b32_e32 v98, v0
	v_mov_b32_e32 v99, v0
	v_mov_b32_e32 v100, v0
	v_mov_b32_e32 v101, v0
	v_mov_b32_e32 v102, v0
	v_mov_b32_e32 v103, v0
	v_mov_b32_e32 v112, v0
	v_mov_b32_e32 v113, v0
	v_mov_b32_e32 v114, v0
	v_mov_b32_e32 v115, v0
	v_mov_b32_e32 v116, v0
	v_mov_b32_e32 v117, v0
	v_mov_b32_e32 v118, v0
	v_mov_b32_e32 v119, v0
	v_mov_b32_e32 v72, v0
	v_mov_b32_e32 v73, v0
	v_mov_b32_e32 v74, v0
	v_mov_b32_e32 v75, v0
	v_mov_b32_e32 v76, v0
	v_mov_b32_e32 v77, v0
	v_mov_b32_e32 v78, v0
	v_mov_b32_e32 v79, v0
	v_mov_b32_e32 v88, v0
	v_mov_b32_e32 v89, v0
	v_mov_b32_e32 v90, v0
	v_mov_b32_e32 v91, v0
	v_mov_b32_e32 v92, v0
	v_mov_b32_e32 v93, v0
	v_mov_b32_e32 v94, v0
	v_mov_b32_e32 v95, v0
	v_mov_b32_e32 v104, v0
	v_mov_b32_e32 v105, v0
	v_mov_b32_e32 v106, v0
	v_mov_b32_e32 v107, v0
	v_mov_b32_e32 v108, v0
	v_mov_b32_e32 v109, v0
	v_mov_b32_e32 v110, v0
	v_mov_b32_e32 v111, v0
	v_mov_b32_e32 v124, v0
	v_mov_b32_e32 v125, v0
	v_mov_b32_e32 v126, v0
	v_mov_b32_e32 v127, v0
	v_mov_b32_e32 v120, v0
	v_mov_b32_e32 v121, v0
	v_mov_b32_e32 v122, v0
	v_mov_b32_e32 v123, v0

; template <class Epi>
; __device__ __forceinline__ void gemm_phase(LAS unsigned char* lds, const int tid, const Gemm g, const StaticOrder& S, const Epi& E) {
;     ...
;         const bool has_next = S.next(ui + 1, nxt);
;         const char* nA = has_next ? (const char*)g.A + (size_t)nxt.pm * tstepA + (size_t)(nxt.pn >> g.a_grp_shift) * g.a_grp_bytes : cA;
;         const char* nB = has_next ? (const char*)g.Bt + (size_t)nxt.pn * tstepB : cB;
;         for (int t = 0; t < nt; t += 2) {
;             const bool last = (t == nt - 2);
;             const char* a1 = cA + (size_t)(t + 1) * kstep;
;             const char* a2 = last ? nA : cA + (size_t)(t + 2) * kstep; const char* b2 = last ? nB : cB + (size_t)(t + 2) * kstep;
;             const char* a3 = a2 + kstep; const char* b3 = b2 + kstep;
;             if constexpr (Epi::SS_LDS) { if (last) {
;                 const char* sp = (const char*)E.ss + (size_t)cur.pm * (256 * 64) + (size_t)tid * 16;
;     ...
; #pragma unroll
;         for (int a = 0; a < 2; ++a)
; #pragma unroll
;             for (int b = 0; b < 2; ++b)
; #pragma unroll
;                 for (int m = 0; m < 4; ++m)
; #pragma unroll
;                     for (int n = 0; n < 2; ++n) acc[a][b][m][n] = (f32x4){0.f, 0.f, 0.f, 0.f};
.LBB0_1030:
	s_ashr_i32 s29, s28, 31
	s_lshl_b64 s[30:31], s[28:29], 19
	s_add_u32 s30, s8, s30
	s_addc_u32 s31, s9, s31
	s_ashr_i32 s27, s26, 31
	s_lshl_b64 s[34:35], s[26:27], 19
	s_add_u32 s34, s45, s34
	v_mov_b32_e32 v127, 0
	s_addc_u32 s35, s46, s35
	s_andn2_b64 vcc, exec, s[22:23]
	s_cbranch_vccz .Lzskip_6
	v_mov_b32_e32 v126, v127
	v_mov_b32_e32 v125, v127
	v_mov_b32_e32 v124, v127
	v_mov_b32_e32 v123, v127
	v_mov_b32_e32 v122, v127
	v_mov_b32_e32 v121, v127
	v_mov_b32_e32 v120, v127
	v_mov_b32_e32 v111, v127
	v_mov_b32_e32 v110, v127
	v_mov_b32_e32 v109, v127
	v_mov_b32_e32 v108, v127
	v_mov_b32_e32 v107, v127
	v_mov_b32_e32 v106, v127
	v_mov_b32_e32 v105, v127
	v_mov_b32_e32 v104, v127
	v_mov_b32_e32 v95, v127
	v_mov_b32_e32 v94, v127
	v_mov_b32_e32 v93, v127
	v_mov_b32_e32 v92, v127
	v_mov_b32_e32 v91, v127
	v_mov_b32_e32 v90, v127
	v_mov_b32_e32 v89, v127
	v_mov_b32_e32 v88, v127
	v_mov_b32_e32 v79, v127
	v_mov_b32_e32 v78, v127
	v_mov_b32_e32 v77, v127
	v_mov_b32_e32 v76, v127
	v_mov_b32_e32 v75, v127
	v_mov_b32_e32 v74, v127
	v_mov_b32_e32 v73, v127
	v_mov_b32_e32 v72, v127
	v_mov_b32_e32 v119, v127
	v_mov_b32_e32 v118, v127
	v_mov_b32_e32 v117, v127
	v_mov_b32_e32 v116, v127
	v_mov_b32_e32 v115, v127
	v_mov_b32_e32 v114, v127
	v_mov_b32_e32 v113, v127
	v_mov_b32_e32 v112, v127
	v_mov_b32_e32 v103, v127
	v_mov_b32_e32 v102, v127
	v_mov_b32_e32 v101, v127
	v_mov_b32_e32 v100, v127
	v_mov_b32_e32 v99, v127
	v_mov_b32_e32 v98, v127
	v_mov_b32_e32 v97, v127
	v_mov_b32_e32 v96, v127
	v_mov_b32_e32 v87, v127
	v_mov_b32_e32 v86, v127
	v_mov_b32_e32 v85, v127
	v_mov_b32_e32 v84, v127
	v_mov_b32_e32 v83, v127
	v_mov_b32_e32 v82, v127
	v_mov_b32_e32 v81, v127
	v_mov_b32_e32 v80, v127
	v_mov_b32_e32 v71, v127
	v_mov_b32_e32 v70, v127
	v_mov_b32_e32 v69, v127
	v_mov_b32_e32 v68, v127
	v_mov_b32_e32 v67, v127
	v_mov_b32_e32 v66, v127
	v_mov_b32_e32 v65, v127
	v_mov_b32_e32 v64, v127
	v_mov_b32_e32 v63, v127
	v_mov_b32_e32 v62, v127
	v_mov_b32_e32 v61, v127
	v_mov_b32_e32 v60, v127
	v_mov_b32_e32 v59, v127
	v_mov_b32_e32 v58, v127
	v_mov_b32_e32 v57, v127
	v_mov_b32_e32 v56, v127
	v_mov_b32_e32 v47, v127
	v_mov_b32_e32 v46, v127
	v_mov_b32_e32 v45, v127
	v_mov_b32_e32 v44, v127
	v_mov_b32_e32 v43, v127
	v_mov_b32_e32 v42, v127
	v_mov_b32_e32 v41, v127
	v_mov_b32_e32 v40, v127
	v_mov_b32_e32 v31, v127
	v_mov_b32_e32 v30, v127
	v_mov_b32_e32 v29, v127
	v_mov_b32_e32 v28, v127
	v_mov_b32_e32 v27, v127
	v_mov_b32_e32 v26, v127
	v_mov_b32_e32 v25, v127
	v_mov_b32_e32 v24, v127
	v_mov_b32_e32 v15, v127
	v_mov_b32_e32 v14, v127
	v_mov_b32_e32 v13, v127
	v_mov_b32_e32 v12, v127
	v_mov_b32_e32 v11, v127
	v_mov_b32_e32 v10, v127
	v_mov_b32_e32 v9, v127
	v_mov_b32_e32 v8, v127
	v_mov_b32_e32 v55, v127
	v_mov_b32_e32 v54, v127
	v_mov_b32_e32 v53, v127
	v_mov_b32_e32 v52, v127
	v_mov_b32_e32 v51, v127
	v_mov_b32_e32 v50, v127
	v_mov_b32_e32 v49, v127
	v_mov_b32_e32 v48, v127
	v_mov_b32_e32 v39, v127
	v_mov_b32_e32 v38, v127
	v_mov_b32_e32 v37, v127
	v_mov_b32_e32 v36, v127
	v_mov_b32_e32 v35, v127
	v_mov_b32_e32 v34, v127
	v_mov_b32_e32 v33, v127
	v_mov_b32_e32 v32, v127
	v_mov_b32_e32 v23, v127
	v_mov_b32_e32 v22, v127
	v_mov_b32_e32 v21, v127
	v_mov_b32_e32 v20, v127
	v_mov_b32_e32 v19, v127
	v_mov_b32_e32 v18, v127
	v_mov_b32_e32 v17, v127
	v_mov_b32_e32 v16, v127
	v_mov_b32_e32 v7, v127
	v_mov_b32_e32 v6, v127
	v_mov_b32_e32 v5, v127
	v_mov_b32_e32 v4, v127
	v_mov_b32_e32 v3, v127
	v_mov_b32_e32 v2, v127
	v_mov_b32_e32 v1, v127
	v_mov_b32_e32 v0, v127
	s_cbranch_vccnz .LBB0_1035
.Lzskip_6:
	s_and_b64 s[42:43], s[4:5], exec
	s_cselect_b32 s27, s31, s41
	s_cselect_b32 s29, s30, s40
	s_cselect_b32 s33, s35, s39
	s_cselect_b32 s62, s34, s38
	s_ashr_i32 s37, s36, 31
	s_lshl_b64 s[42:43], s[36:37], 14
	s_add_u32 s37, s38, 0x100
	s_addc_u32 s63, s39, 0
	v_lshl_add_u64 v[128:129], v[188:189], 0, s[42:43]
	s_add_u32 s38, s40, 0x40080
	v_mov_b32_e32 v0, 0
	v_lshl_add_u64 v[130:131], v[128:129], 0, s[6:7]
	s_addc_u32 s39, s41, 0
	s_mov_b32 s64, 0
	v_mov_b32_e32 v1, v0
	v_mov_b32_e32 v2, v0
	v_mov_b32_e32 v3, v0
	v_mov_b32_e32 v4, v0
	v_mov_b32_e32 v5, v0
	v_mov_b32_e32 v6, v0
	v_mov_b32_e32 v7, v0
	v_mov_b32_e32 v16, v0
	v_mov_b32_e32 v17, v0
	v_mov_b32_e32 v18, v0
	v_mov_b32_e32 v19, v0
	v_mov_b32_e32 v20, v0
	v_mov_b32_e32 v21, v0
	v_mov_b32_e32 v22, v0
	v_mov_b32_e32 v23, v0
	v_mov_b32_e32 v32, v0
	v_mov_b32_e32 v33, v0
	v_mov_b32_e32 v34, v0
	v_mov_b32_e32 v35, v0
	v_mov_b32_e32 v36, v0
	v_mov_b32_e32 v37, v0
	v_mov_b32_e32 v38, v0
	v_mov_b32_e32 v39, v0
	v_mov_b32_e32 v48, v0
	v_mov_b32_e32 v49, v0
	v_mov_b32_e32 v50, v0
	v_mov_b32_e32 v51, v0
	v_mov_b32_e32 v52, v0
	v_mov_b32_e32 v53, v0
	v_mov_b32_e32 v54, v0
	v_mov_b32_e32 v55, v0
	v_mov_b32_e32 v8, v0
	v_mov_b32_e32 v9, v0
	v_mov_b32_e32 v10, v0
	v_mov_b32_e32 v11, v0
	v_mov_b32_e32 v12, v0
	v_mov_b32_e32 v13, v0
	v_mov_b32_e32 v14, v0
	v_mov_b32_e32 v15, v0
	v_mov_b32_e32 v24, v0
	v_mov_b32_e32 v25, v0
	v_mov_b32_e32 v26, v0
	v_mov_b32_e32 v27, v0
	v_mov_b32_e32 v28, v0
	v_mov_b32_e32 v29, v0
	v_mov_b32_e32 v30, v0
	v_mov_b32_e32 v31, v0
	v_mov_b32_e32 v40, v0
	v_mov_b32_e32 v41, v0
	v_mov_b32_e32 v42, v0
	v_mov_b32_e32 v43, v0
	v_mov_b32_e32 v44, v0
	v_mov_b32_e32 v45, v0
	v_mov_b32_e32 v46, v0
	v_mov_b32_e32 v47, v0
	v_mov_b32_e32 v56, v0
	v_mov_b32_e32 v57, v0
	v_mov_b32_e32 v58, v0
	v_mov_b32_e32 v59, v0
	v_mov_b32_e32 v60, v0
	v_mov_b32_e32 v61, v0
	v_mov_b32_e32 v62, v0
	v_mov_b32_e32 v63, v0
	v_mov_b32_e32 v64, v0
	v_mov_b32_e32 v65, v0
	v_mov_b32_e32 v66, v0
	v_mov_b32_e32 v67, v0
	v_mov_b32_e32 v68, v0
	v_mov_b32_e32 v69, v0
	v_mov_b32_e32 v70, v0
	v_mov_b32_e32 v71, v0
	v_mov_b32_e32 v80, v0
	v_mov_b32_e32 v81, v0
	v_mov_b32_e32 v82, v0
	v_mov_b32_e32 v83, v0
	v_mov_b32_e32 v84, v0
	v_mov_b32_e32 v85, v0
	v_mov_b32_e32 v86, v0
	v_mov_b32_e32 v87, v0
	v_mov_b32_e32 v96, v0
	v_mov_b32_e32 v97, v0
	v_mov_b32_e32 v98, v0
	v_mov_b32_e32 v99, v0
	v_mov_b32_e32 v100, v0
	v_mov_b32_e32 v101, v0
	v_mov_b32_e32 v102, v0
	v_mov_b32_e32 v103, v0
	v_mov_b32_e32 v112, v0
	v_mov_b32_e32 v113, v0
	v_mov_b32_e32 v114, v0
	v_mov_b32_e32 v115, v0
	v_mov_b32_e32 v116, v0
	v_mov_b32_e32 v117, v0
	v_mov_b32_e32 v118, v0
	v_mov_b32_e32 v119, v0
	v_mov_b32_e32 v72, v0
	v_mov_b32_e32 v73, v0
	v_mov_b32_e32 v74, v0
	v_mov_b32_e32 v75, v0
	v_mov_b32_e32 v76, v0
	v_mov_b32_e32 v77, v0
	v_mov_b32_e32 v78, v0
	v_mov_b32_e32 v79, v0
	v_mov_b32_e32 v88, v0
	v_mov_b32_e32 v89, v0
	v_mov_b32_e32 v90, v0
	v_mov_b32_e32 v91, v0
	v_mov_b32_e32 v92, v0
	v_mov_b32_e32 v93, v0
	v_mov_b32_e32 v94, v0
	v_mov_b32_e32 v95, v0
	v_mov_b32_e32 v104, v0
	v_mov_b32_e32 v105, v0
	v_mov_b32_e32 v106, v0
	v_mov_b32_e32 v107, v0
	v_mov_b32_e32 v108, v0
	v_mov_b32_e32 v109, v0
	v_mov_b32_e32 v110, v0
	v_mov_b32_e32 v111, v0
	v_mov_b32_e32 v120, v0
	v_mov_b32_e32 v121, v0
	v_mov_b32_e32 v122, v0
	v_mov_b32_e32 v123, v0
	v_mov_b32_e32 v124, v0
	v_mov_b32_e32 v125, v0
	v_mov_b32_e32 v126, v0
	v_mov_b32_e32 v127, v0
	s_branch .LBB0_1033

; template <class Epi>
; __device__ __forceinline__ void gemm_phase(LAS unsigned char* lds, const int tid, const Gemm g, const StaticOrder& S, const Epi& E) {
;     ...
;         const bool has_next = S.next(ui + 1, nxt);
;         const char* nA = has_next ? (const char*)g.A + (size_t)nxt.pm * tstepA + (size_t)(nxt.pn >> g.a_grp_shift) * g.a_grp_bytes : cA;
;         const char* nB = has_next ? (const char*)g.Bt + (size_t)nxt.pn * tstepB : cB;
;         for (int t = 0; t < nt; t += 2) {
;             const bool last = (t == nt - 2);
;             const char* a1 = cA + (size_t)(t + 1) * kstep;
;             const char* a2 = last ? nA : cA + (size_t)(t + 2) * kstep; const char* b2 = last ? nB : cB + (size_t)(t + 2) * kstep;
;             const char* a3 = a2 + kstep; const char* b3 = b2 + kstep;
;             if constexpr (Epi::SS_LDS) { if (last) {
;                 const char* sp = (const char*)E.ss + (size_t)cur.pm * (256 * 64) + (size_t)tid * 16;
;     ...
; #pragma unroll
;         for (int a = 0; a < 2; ++a)
; #pragma unroll
;             for (int b = 0; b < 2; ++b)
; #pragma unroll
;                 for (int m = 0; m < 4; ++m)
; #pragma unroll
;                     for (int n = 0; n < 2; ++n) acc[a][b][m][n] = (f32x4){0.f, 0.f, 0.f, 0.f};
.LBB0_1310:
	s_ashr_i32 s21, s20, 31
	s_lshl_b64 s[22:23], s[20:21], 19
	s_add_u32 s22, s37, s22
	s_addc_u32 s23, s38, s23
	s_ashr_i32 s19, s18, 31
	s_lshl_b64 s[24:25], s[18:19], 19
	s_add_u32 s24, s39, s24
	v_mov_b32_e32 v127, 0
	s_addc_u32 s25, s40, s25
	s_andn2_b64 vcc, exec, s[12:13]
	s_cbranch_vccz .Lzskip_8
	v_mov_b32_e32 v126, v127
	v_mov_b32_e32 v125, v127
	v_mov_b32_e32 v124, v127
	v_mov_b32_e32 v123, v127
	v_mov_b32_e32 v122, v127
	v_mov_b32_e32 v121, v127
	v_mov_b32_e32 v120, v127
	v_mov_b32_e32 v111, v127
	v_mov_b32_e32 v110, v127
	v_mov_b32_e32 v109, v127
	v_mov_b32_e32 v108, v127
	v_mov_b32_e32 v107, v127
	v_mov_b32_e32 v106, v127
	v_mov_b32_e32 v105, v127
	v_mov_b32_e32 v104, v127
	v_mov_b32_e32 v95, v127
	v_mov_b32_e32 v94, v127
	v_mov_b32_e32 v93, v127
	v_mov_b32_e32 v92, v127
	v_mov_b32_e32 v91, v127
	v_mov_b32_e32 v90, v127
	v_mov_b32_e32 v89, v127
	v_mov_b32_e32 v88, v127
	v_mov_b32_e32 v79, v127
	v_mov_b32_e32 v78, v127
	v_mov_b32_e32 v77, v127
	v_mov_b32_e32 v76, v127
	v_mov_b32_e32 v75, v127
	v_mov_b32_e32 v74, v127
	v_mov_b32_e32 v73, v127
	v_mov_b32_e32 v72, v127
	v_mov_b32_e32 v119, v127
	v_mov_b32_e32 v118, v127
	v_mov_b32_e32 v117, v127
	v_mov_b32_e32 v116, v127
	v_mov_b32_e32 v115, v127
	v_mov_b32_e32 v114, v127
	v_mov_b32_e32 v113, v127
	v_mov_b32_e32 v112, v127
	v_mov_b32_e32 v103, v127
	v_mov_b32_e32 v102, v127
	v_mov_b32_e32 v101, v127
	v_mov_b32_e32 v100, v127
	v_mov_b32_e32 v99, v127
	v_mov_b32_e32 v98, v127
	v_mov_b32_e32 v97, v127
	v_mov_b32_e32 v96, v127
	v_mov_b32_e32 v87, v127
	v_mov_b32_e32 v86, v127
	v_mov_b32_e32 v85, v127
	v_mov_b32_e32 v84, v127
	v_mov_b32_e32 v83, v127
	v_mov_b32_e32 v82, v127
	v_mov_b32_e32 v81, v127
	v_mov_b32_e32 v80, v127
	v_mov_b32_e32 v71, v127
	v_mov_b32_e32 v70, v127
	v_mov_b32_e32 v69, v127
	v_mov_b32_e32 v68, v127
	v_mov_b32_e32 v67, v127
	v_mov_b32_e32 v66, v127
	v_mov_b32_e32 v65, v127
	v_mov_b32_e32 v64, v127
	v_mov_b32_e32 v63, v127
	v_mov_b32_e32 v62, v127
	v_mov_b32_e32 v61, v127
	v_mov_b32_e32 v60, v127
	v_mov_b32_e32 v59, v127
	v_mov_b32_e32 v58, v127
	v_mov_b32_e32 v57, v127
	v_mov_b32_e32 v56, v127
	v_mov_b32_e32 v47, v127
	v_mov_b32_e32 v46, v127
	v_mov_b32_e32 v45, v127
	v_mov_b32_e32 v44, v127
	v_mov_b32_e32 v43, v127
	v_mov_b32_e32 v42, v127
	v_mov_b32_e32 v41, v127
	v_mov_b32_e32 v40, v127
	v_mov_b32_e32 v31, v127
	v_mov_b32_e32 v30, v127
	v_mov_b32_e32 v29, v127
	v_mov_b32_e32 v28, v127
	v_mov_b32_e32 v27, v127
	v_mov_b32_e32 v26, v127
	v_mov_b32_e32 v25, v127
	v_mov_b32_e32 v24, v127
	v_mov_b32_e32 v15, v127
	v_mov_b32_e32 v14, v127
	v_mov_b32_e32 v13, v127
	v_mov_b32_e32 v12, v127
	v_mov_b32_e32 v11, v127
	v_mov_b32_e32 v10, v127
	v_mov_b32_e32 v9, v127
	v_mov_b32_e32 v8, v127
	v_mov_b32_e32 v55, v127
	v_mov_b32_e32 v54, v127
	v_mov_b32_e32 v53, v127
	v_mov_b32_e32 v52, v127
	v_mov_b32_e32 v51, v127
	v_mov_b32_e32 v50, v127
	v_mov_b32_e32 v49, v127
	v_mov_b32_e32 v48, v127
	v_mov_b32_e32 v39, v127
	v_mov_b32_e32 v38, v127
	v_mov_b32_e32 v37, v127
	v_mov_b32_e32 v36, v127
	v_mov_b32_e32 v35, v127
	v_mov_b32_e32 v34, v127
	v_mov_b32_e32 v33, v127
	v_mov_b32_e32 v32, v127
	v_mov_b32_e32 v23, v127
	v_mov_b32_e32 v22, v127
	v_mov_b32_e32 v21, v127
	v_mov_b32_e32 v20, v127
	v_mov_b32_e32 v19, v127
	v_mov_b32_e32 v18, v127
	v_mov_b32_e32 v17, v127
	v_mov_b32_e32 v16, v127
	v_mov_b32_e32 v7, v127
	v_mov_b32_e32 v6, v127
	v_mov_b32_e32 v5, v127
	v_mov_b32_e32 v4, v127
	v_mov_b32_e32 v3, v127
	v_mov_b32_e32 v2, v127
	v_mov_b32_e32 v1, v127
	v_mov_b32_e32 v0, v127
	s_cbranch_vccnz .LBB0_1315
.Lzskip_8:
	s_and_b64 s[34:35], s[2:3], exec
	s_cselect_b32 s19, s23, s31
	s_cselect_b32 s21, s22, s30
	s_cselect_b32 s33, s25, s29
	s_cselect_b32 s56, s24, s28
	s_ashr_i32 s5, s4, 31
	s_lshl_b64 s[34:35], s[4:5], 14
	s_add_u32 s5, s28, 0x100
	s_addc_u32 s57, s29, 0
	v_lshl_add_u64 v[148:149], v[138:139], 0, s[34:35]
	s_add_u32 s28, s30, 0x40080
	v_mov_b32_e32 v0, 0
	v_lshl_add_u64 v[150:151], v[148:149], 0, s[16:17]
	s_addc_u32 s29, s31, 0
	s_mov_b32 s58, 0
	v_mov_b32_e32 v1, v0
	v_mov_b32_e32 v2, v0
	v_mov_b32_e32 v3, v0
	v_mov_b32_e32 v4, v0
	v_mov_b32_e32 v5, v0
	v_mov_b32_e32 v6, v0
	v_mov_b32_e32 v7, v0
	v_mov_b32_e32 v16, v0
	v_mov_b32_e32 v17, v0
	v_mov_b32_e32 v18, v0
	v_mov_b32_e32 v19, v0
	v_mov_b32_e32 v20, v0
	v_mov_b32_e32 v21, v0
	v_mov_b32_e32 v22, v0
	v_mov_b32_e32 v23, v0
	v_mov_b32_e32 v32, v0
	v_mov_b32_e32 v33, v0
	v_mov_b32_e32 v34, v0
	v_mov_b32_e32 v35, v0
	v_mov_b32_e32 v36, v0
	v_mov_b32_e32 v37, v0
	v_mov_b32_e32 v38, v0
	v_mov_b32_e32 v39, v0
	v_mov_b32_e32 v48, v0
	v_mov_b32_e32 v49, v0
	v_mov_b32_e32 v50, v0
	v_mov_b32_e32 v51, v0
	v_mov_b32_e32 v52, v0
	v_mov_b32_e32 v53, v0
	v_mov_b32_e32 v54, v0
	v_mov_b32_e32 v55, v0
	v_mov_b32_e32 v8, v0
	v_mov_b32_e32 v9, v0
	v_mov_b32_e32 v10, v0
	v_mov_b32_e32 v11, v0
	v_mov_b32_e32 v12, v0
	v_mov_b32_e32 v13, v0
	v_mov_b32_e32 v14, v0
	v_mov_b32_e32 v15, v0
	v_mov_b32_e32 v24, v0
	v_mov_b32_e32 v25, v0
	v_mov_b32_e32 v26, v0
	v_mov_b32_e32 v27, v0
	v_mov_b32_e32 v28, v0
	v_mov_b32_e32 v29, v0
	v_mov_b32_e32 v30, v0
	v_mov_b32_e32 v31, v0
	v_mov_b32_e32 v40, v0
	v_mov_b32_e32 v41, v0
	v_mov_b32_e32 v42, v0
	v_mov_b32_e32 v43, v0
	v_mov_b32_e32 v44, v0
	v_mov_b32_e32 v45, v0
	v_mov_b32_e32 v46, v0
	v_mov_b32_e32 v47, v0
	v_mov_b32_e32 v56, v0
	v_mov_b32_e32 v57, v0
	v_mov_b32_e32 v58, v0
	v_mov_b32_e32 v59, v0
	v_mov_b32_e32 v60, v0
	v_mov_b32_e32 v61, v0
	v_mov_b32_e32 v62, v0
	v_mov_b32_e32 v63, v0
	v_mov_b32_e32 v64, v0
	v_mov_b32_e32 v65, v0
	v_mov_b32_e32 v66, v0
	v_mov_b32_e32 v67, v0
	v_mov_b32_e32 v68, v0
	v_mov_b32_e32 v69, v0
	v_mov_b32_e32 v70, v0
	v_mov_b32_e32 v71, v0
	v_mov_b32_e32 v80, v0
	v_mov_b32_e32 v81, v0
	v_mov_b32_e32 v82, v0
	v_mov_b32_e32 v83, v0
	v_mov_b32_e32 v84, v0
	v_mov_b32_e32 v85, v0
	v_mov_b32_e32 v86, v0
	v_mov_b32_e32 v87, v0
	v_mov_b32_e32 v96, v0
	v_mov_b32_e32 v97, v0
	v_mov_b32_e32 v98, v0
	v_mov_b32_e32 v99, v0
	v_mov_b32_e32 v100, v0
	v_mov_b32_e32 v101, v0
	v_mov_b32_e32 v102, v0
	v_mov_b32_e32 v103, v0
	v_mov_b32_e32 v112, v0
	v_mov_b32_e32 v113, v0
	v_mov_b32_e32 v114, v0
	v_mov_b32_e32 v115, v0
	v_mov_b32_e32 v116, v0
	v_mov_b32_e32 v117, v0
	v_mov_b32_e32 v118, v0
	v_mov_b32_e32 v119, v0
	v_mov_b32_e32 v72, v0
	v_mov_b32_e32 v73, v0
	v_mov_b32_e32 v74, v0
	v_mov_b32_e32 v75, v0
	v_mov_b32_e32 v76, v0
	v_mov_b32_e32 v77, v0
	v_mov_b32_e32 v78, v0
	v_mov_b32_e32 v79, v0
	v_mov_b32_e32 v88, v0
	v_mov_b32_e32 v89, v0
	v_mov_b32_e32 v90, v0
	v_mov_b32_e32 v91, v0
	v_mov_b32_e32 v92, v0
	v_mov_b32_e32 v93, v0
	v_mov_b32_e32 v94, v0
	v_mov_b32_e32 v95, v0
	v_mov_b32_e32 v104, v0
	v_mov_b32_e32 v105, v0
	v_mov_b32_e32 v106, v0
	v_mov_b32_e32 v107, v0
	v_mov_b32_e32 v108, v0
	v_mov_b32_e32 v109, v0
	v_mov_b32_e32 v110, v0
	v_mov_b32_e32 v111, v0
	v_mov_b32_e32 v120, v0
	v_mov_b32_e32 v121, v0
	v_mov_b32_e32 v122, v0
	v_mov_b32_e32 v123, v0
	v_mov_b32_e32 v124, v0
	v_mov_b32_e32 v125, v0
	v_mov_b32_e32 v126, v0
	v_mov_b32_e32 v127, v0
	s_branch .LBB0_1313

; template <class Epi>
; __device__ __forceinline__ void gemm_phase(LAS unsigned char* lds, const int tid, const Gemm g, const StaticOrder& S, const Epi& E) {
;     ...
;     const char* cA = (const char*)g.A + (size_t)cur.pm * tstepA + (size_t)(cur.pn >> g.a_grp_shift) * g.a_grp_bytes;
;     ...
;         const bool has_next = S.next(ui + 1, nxt);
;         const char* nA = has_next ? (const char*)g.A + (size_t)nxt.pm * tstepA + (size_t)(nxt.pn >> g.a_grp_shift) * g.a_grp_bytes : cA;
;         const char* nB = has_next ? (const char*)g.Bt + (size_t)nxt.pn * tstepB : cB;
;         for (int t = 0; t < nt; t += 2) {
;             const bool last = (t == nt - 2);
;             const char* a1 = cA + (size_t)(t + 1) * kstep;
;             const char* a2 = last ? nA : cA + (size_t)(t + 2) * kstep; const char* b2 = last ? nB : cB + (size_t)(t + 2) * kstep;
;             const char* a3 = a2 + kstep; const char* b3 = b2 + kstep;
;             if constexpr (Epi::SS_LDS) { if (last) {
;                 const char* sp = (const char*)E.ss + (size_t)cur.pm * (256 * 64) + (size_t)tid * 16;
;     ...
; #pragma unroll
;         for (int a = 0; a < 2; ++a)
; #pragma unroll
;             for (int b = 0; b < 2; ++b)
; #pragma unroll
;                 for (int m = 0; m < 4; ++m)
; #pragma unroll
;                     for (int n = 0; n < 2; ++n) acc[a][b][m][n] = (f32x4){0.f, 0.f, 0.f, 0.f};
.LBB0_1523:
	s_ashr_i32 s29, s28, 31
	s_lshl_b64 s[30:31], s[28:29], 19
	s_add_u32 s27, s8, s30
	s_addc_u32 s29, s9, s31
	s_ashr_i32 s30, s26, 1
	s_ashr_i32 s31, s30, 31
	s_lshl_b64 s[30:31], s[30:31], 9
	s_add_u32 s30, s27, s30
	s_addc_u32 s31, s29, s31
	s_ashr_i32 s27, s26, 31
	s_lshl_b64 s[34:35], s[26:27], 17
	s_add_u32 s34, s44, s34
	v_mov_b32_e32 v171, 0
	s_addc_u32 s35, s45, s35
	s_andn2_b64 vcc, exec, s[22:23]
	s_cbranch_vccz .Lzskip_9
	v_mov_b32_e32 v170, v171
	v_mov_b32_e32 v169, v171
	v_mov_b32_e32 v168, v171
	v_mov_b32_e32 v159, v171
	v_mov_b32_e32 v158, v171
	v_mov_b32_e32 v157, v171
	v_mov_b32_e32 v156, v171
	v_mov_b32_e32 v151, v171
	v_mov_b32_e32 v150, v171
	v_mov_b32_e32 v149, v171
	v_mov_b32_e32 v148, v171
	v_mov_b32_e32 v139, v171
	v_mov_b32_e32 v138, v171
	v_mov_b32_e32 v137, v171
	v_mov_b32_e32 v136, v171
	v_mov_b32_e32 v131, v171
	v_mov_b32_e32 v130, v171
	v_mov_b32_e32 v129, v171
	v_mov_b32_e32 v128, v171
	v_mov_b32_e32 v119, v171
	v_mov_b32_e32 v118, v171
	v_mov_b32_e32 v117, v171
	v_mov_b32_e32 v116, v171
	v_mov_b32_e32 v111, v171
	v_mov_b32_e32 v110, v171
	v_mov_b32_e32 v109, v171
	v_mov_b32_e32 v108, v171
	v_mov_b32_e32 v99, v171
	v_mov_b32_e32 v98, v171
	v_mov_b32_e32 v97, v171
	v_mov_b32_e32 v96, v171
	v_mov_b32_e32 v167, v171
	v_mov_b32_e32 v166, v171
	v_mov_b32_e32 v165, v171
	v_mov_b32_e32 v164, v171
	v_mov_b32_e32 v155, v171
	v_mov_b32_e32 v154, v171
	v_mov_b32_e32 v153, v171
	v_mov_b32_e32 v152, v171
	v_mov_b32_e32 v147, v171
	v_mov_b32_e32 v146, v171
	v_mov_b32_e32 v145, v171
	v_mov_b32_e32 v144, v171
	v_mov_b32_e32 v135, v171
	v_mov_b32_e32 v134, v171
	v_mov_b32_e32 v133, v171
	v_mov_b32_e32 v132, v171
	v_mov_b32_e32 v127, v171
	v_mov_b32_e32 v126, v171
	v_mov_b32_e32 v125, v171
	v_mov_b32_e32 v124, v171
	v_mov_b32_e32 v115, v171
	v_mov_b32_e32 v114, v171
	v_mov_b32_e32 v113, v171
	v_mov_b32_e32 v112, v171
	v_mov_b32_e32 v107, v171
	v_mov_b32_e32 v106, v171
	v_mov_b32_e32 v105, v171
	v_mov_b32_e32 v104, v171
	v_mov_b32_e32 v95, v171
	v_mov_b32_e32 v94, v171
	v_mov_b32_e32 v93, v171
	v_mov_b32_e32 v92, v171
	v_mov_b32_e32 v91, v171
	v_mov_b32_e32 v90, v171
	v_mov_b32_e32 v89, v171
	v_mov_b32_e32 v88, v171
	v_mov_b32_e32 v79, v171
	v_mov_b32_e32 v78, v171
	v_mov_b32_e32 v77, v171
	v_mov_b32_e32 v76, v171
	v_mov_b32_e32 v59, v171
	v_mov_b32_e32 v58, v171
	v_mov_b32_e32 v57, v171
	v_mov_b32_e32 v56, v171
	v_mov_b32_e32 v39, v171
	v_mov_b32_e32 v38, v171
	v_mov_b32_e32 v37, v171
	v_mov_b32_e32 v36, v171
	v_mov_b32_e32 v31, v171
	v_mov_b32_e32 v30, v171
	v_mov_b32_e32 v29, v171
	v_mov_b32_e32 v28, v171
	v_mov_b32_e32 v23, v171
	v_mov_b32_e32 v22, v171
	v_mov_b32_e32 v21, v171
	v_mov_b32_e32 v20, v171
	v_mov_b32_e32 v15, v171
	v_mov_b32_e32 v14, v171
	v_mov_b32_e32 v13, v171
	v_mov_b32_e32 v12, v171
	v_mov_b32_e32 v7, v171
	v_mov_b32_e32 v6, v171
	v_mov_b32_e32 v5, v171
	v_mov_b32_e32 v4, v171
	v_mov_b32_e32 v87, v171
	v_mov_b32_e32 v86, v171
	v_mov_b32_e32 v85, v171
	v_mov_b32_e32 v84, v171
	v_mov_b32_e32 v75, v171
	v_mov_b32_e32 v74, v171
	v_mov_b32_e32 v73, v171
	v_mov_b32_e32 v72, v171
	v_mov_b32_e32 v47, v171
	v_mov_b32_e32 v46, v171
	v_mov_b32_e32 v45, v171
	v_mov_b32_e32 v44, v171
	v_mov_b32_e32 v35, v171
	v_mov_b32_e32 v34, v171
	v_mov_b32_e32 v33, v171
	v_mov_b32_e32 v32, v171
	v_mov_b32_e32 v27, v171
	v_mov_b32_e32 v26, v171
	v_mov_b32_e32 v25, v171
	v_mov_b32_e32 v24, v171
	v_mov_b32_e32 v19, v171
	v_mov_b32_e32 v18, v171
	v_mov_b32_e32 v17, v171
	v_mov_b32_e32 v16, v171
	v_mov_b32_e32 v11, v171
	v_mov_b32_e32 v10, v171
	v_mov_b32_e32 v9, v171
	v_mov_b32_e32 v8, v171
	v_mov_b32_e32 v3, v171
	v_mov_b32_e32 v2, v171
	v_mov_b32_e32 v1, v171
	v_mov_b32_e32 v0, v171
	s_cbranch_vccnz .LBB0_1526
.Lzskip_9:
	s_and_b64 s[40:41], s[2:3], exec
	s_cselect_b32 s27, s31, s39
	s_cselect_b32 s29, s30, s38
	s_cselect_b32 s33, s35, s37
	s_cselect_b32 s61, s34, s36
	s_add_u32 s62, s36, 0x100
	s_addc_u32 s63, s37, 0
	s_add_u32 s36, s38, 0x40080
	v_mov_b32_e32 v0, 0
	s_addc_u32 s37, s39, 0
	s_mov_b32 s38, 0
	v_mov_b32_e32 v1, v0
	v_mov_b32_e32 v2, v0
	v_mov_b32_e32 v3, v0
	v_mov_b32_e32 v8, v0
	v_mov_b32_e32 v9, v0
	v_mov_b32_e32 v10, v0
	v_mov_b32_e32 v11, v0
	v_mov_b32_e32 v16, v0
	v_mov_b32_e32 v17, v0
	v_mov_b32_e32 v18, v0
	v_mov_b32_e32 v19, v0
	v_mov_b32_e32 v24, v0
	v_mov_b32_e32 v25, v0
	v_mov_b32_e32 v26, v0
	v_mov_b32_e32 v27, v0
	v_mov_b32_e32 v32, v0
	v_mov_b32_e32 v33, v0
	v_mov_b32_e32 v34, v0
	v_mov_b32_e32 v35, v0
	v_mov_b32_e32 v44, v0
	v_mov_b32_e32 v45, v0
	v_mov_b32_e32 v46, v0
	v_mov_b32_e32 v47, v0
	v_mov_b32_e32 v72, v0
	v_mov_b32_e32 v73, v0
	v_mov_b32_e32 v74, v0
	v_mov_b32_e32 v75, v0
	v_mov_b32_e32 v84, v0
	v_mov_b32_e32 v85, v0
	v_mov_b32_e32 v86, v0
	v_mov_b32_e32 v87, v0
	v_mov_b32_e32 v4, v0
	v_mov_b32_e32 v5, v0
	v_mov_b32_e32 v6, v0
	v_mov_b32_e32 v7, v0
	v_mov_b32_e32 v12, v0
	v_mov_b32_e32 v13, v0
	v_mov_b32_e32 v14, v0
	v_mov_b32_e32 v15, v0
	v_mov_b32_e32 v20, v0
	v_mov_b32_e32 v21, v0
	v_mov_b32_e32 v22, v0
	v_mov_b32_e32 v23, v0
	v_mov_b32_e32 v28, v0
	v_mov_b32_e32 v29, v0
	v_mov_b32_e32 v30, v0
	v_mov_b32_e32 v31, v0
	v_mov_b32_e32 v36, v0
	v_mov_b32_e32 v37, v0
	v_mov_b32_e32 v38, v0
	v_mov_b32_e32 v39, v0
	v_mov_b32_e32 v56, v0
	v_mov_b32_e32 v57, v0
	v_mov_b32_e32 v58, v0
	v_mov_b32_e32 v59, v0
	v_mov_b32_e32 v76, v0
	v_mov_b32_e32 v77, v0
	v_mov_b32_e32 v78, v0
	v_mov_b32_e32 v79, v0
	v_mov_b32_e32 v88, v0
	v_mov_b32_e32 v89, v0
	v_mov_b32_e32 v90, v0
	v_mov_b32_e32 v91, v0
	v_mov_b32_e32 v92, v0
	v_mov_b32_e32 v93, v0
	v_mov_b32_e32 v94, v0
	v_mov_b32_e32 v95, v0
	v_mov_b32_e32 v104, v0
	v_mov_b32_e32 v105, v0
	v_mov_b32_e32 v106, v0
	v_mov_b32_e32 v107, v0
	v_mov_b32_e32 v112, v0
	v_mov_b32_e32 v113, v0
	v_mov_b32_e32 v114, v0
	v_mov_b32_e32 v115, v0
	v_mov_b32_e32 v124, v0
	v_mov_b32_e32 v125, v0
	v_mov_b32_e32 v126, v0
	v_mov_b32_e32 v127, v0
	v_mov_b32_e32 v132, v0
	v_mov_b32_e32 v133, v0
	v_mov_b32_e32 v134, v0
	v_mov_b32_e32 v135, v0
	v_mov_b32_e32 v144, v0
	v_mov_b32_e32 v145, v0
	v_mov_b32_e32 v146, v0
	v_mov_b32_e32 v147, v0
	v_mov_b32_e32 v152, v0
	v_mov_b32_e32 v153, v0
	v_mov_b32_e32 v154, v0
	v_mov_b32_e32 v155, v0
	v_mov_b32_e32 v164, v0
	v_mov_b32_e32 v165, v0
	v_mov_b32_e32 v166, v0
	v_mov_b32_e32 v167, v0
	v_mov_b32_e32 v96, v0
	v_mov_b32_e32 v97, v0
	v_mov_b32_e32 v98, v0
	v_mov_b32_e32 v99, v0
	v_mov_b32_e32 v108, v0
	v_mov_b32_e32 v109, v0
	v_mov_b32_e32 v110, v0
	v_mov_b32_e32 v111, v0
	v_mov_b32_e32 v116, v0
	v_mov_b32_e32 v117, v0
	v_mov_b32_e32 v118, v0
	v_mov_b32_e32 v119, v0
	v_mov_b32_e32 v128, v0
	v_mov_b32_e32 v129, v0
	v_mov_b32_e32 v130, v0
	v_mov_b32_e32 v131, v0
	v_mov_b32_e32 v136, v0
	v_mov_b32_e32 v137, v0
	v_mov_b32_e32 v138, v0
	v_mov_b32_e32 v139, v0
	v_mov_b32_e32 v148, v0
	v_mov_b32_e32 v149, v0
	v_mov_b32_e32 v150, v0
	v_mov_b32_e32 v151, v0
	v_mov_b32_e32 v156, v0
	v_mov_b32_e32 v157, v0
	v_mov_b32_e32 v158, v0
	v_mov_b32_e32 v159, v0
	v_mov_b32_e32 v168, v0
	v_mov_b32_e32 v169, v0
	v_mov_b32_e32 v170, v0
	v_mov_b32_e32 v171, v0

; template <class Epi>
; __device__ __forceinline__ void gemm_phase(LAS unsigned char* lds, const int tid, const Gemm g, const StaticOrder& S, const Epi& E) {
;     ...
;         const bool has_next = S.next(ui + 1, nxt);
;         const char* nA = has_next ? (const char*)g.A + (size_t)nxt.pm * tstepA + (size_t)(nxt.pn >> g.a_grp_shift) * g.a_grp_bytes : cA;
;         const char* nB = has_next ? (const char*)g.Bt + (size_t)nxt.pn * tstepB : cB;
;         for (int t = 0; t < nt; t += 2) {
;             const bool last = (t == nt - 2);
;             const char* a1 = cA + (size_t)(t + 1) * kstep;
;             const char* a2 = last ? nA : cA + (size_t)(t + 2) * kstep; const char* b2 = last ? nB : cB + (size_t)(t + 2) * kstep;
;             const char* a3 = a2 + kstep; const char* b3 = b2 + kstep;
;             if constexpr (Epi::SS_LDS) { if (last) {
;                 const char* sp = (const char*)E.ss + (size_t)cur.pm * (256 * 64) + (size_t)tid * 16;
;     ...
; #pragma unroll
;         for (int a = 0; a < 2; ++a)
; #pragma unroll
;             for (int b = 0; b < 2; ++b)
; #pragma unroll
;                 for (int m = 0; m < 4; ++m)
; #pragma unroll
;                     for (int n = 0; n < 2; ++n) acc[a][b][m][n] = (f32x4){0.f, 0.f, 0.f, 0.f};
.LBB0_1732:
	s_ashr_i32 s27, s26, 31
	s_lshl_b64 s[28:29], s[26:27], 19
	s_add_u32 s28, s8, s28
	s_addc_u32 s29, s9, s29
	s_ashr_i32 s25, s24, 31
	s_lshl_b64 s[30:31], s[24:25], 19
	s_add_u32 s30, s42, s30
	v_mov_b32_e32 v123, 0
	s_addc_u32 s31, s43, s31
	s_andn2_b64 vcc, exec, s[20:21]
	s_cbranch_vccz .Lzskip_10
	v_mov_b32_e32 v122, v123
	v_mov_b32_e32 v121, v123
	v_mov_b32_e32 v120, v123
	v_mov_b32_e32 v127, v123
	v_mov_b32_e32 v126, v123
	v_mov_b32_e32 v125, v123
	v_mov_b32_e32 v124, v123
	v_mov_b32_e32 v111, v123
	v_mov_b32_e32 v110, v123
	v_mov_b32_e32 v109, v123
	v_mov_b32_e32 v108, v123
	v_mov_b32_e32 v107, v123
	v_mov_b32_e32 v106, v123
	v_mov_b32_e32 v105, v123
	v_mov_b32_e32 v104, v123
	v_mov_b32_e32 v95, v123
	v_mov_b32_e32 v94, v123
	v_mov_b32_e32 v93, v123
	v_mov_b32_e32 v92, v123
	v_mov_b32_e32 v91, v123
	v_mov_b32_e32 v90, v123
	v_mov_b32_e32 v89, v123
	v_mov_b32_e32 v88, v123
	v_mov_b32_e32 v79, v123
	v_mov_b32_e32 v78, v123
	v_mov_b32_e32 v77, v123
	v_mov_b32_e32 v76, v123
	v_mov_b32_e32 v75, v123
	v_mov_b32_e32 v74, v123
	v_mov_b32_e32 v73, v123
	v_mov_b32_e32 v72, v123
	v_mov_b32_e32 v119, v123
	v_mov_b32_e32 v118, v123
	v_mov_b32_e32 v117, v123
	v_mov_b32_e32 v116, v123
	v_mov_b32_e32 v115, v123
	v_mov_b32_e32 v114, v123
	v_mov_b32_e32 v113, v123
	v_mov_b32_e32 v112, v123
	v_mov_b32_e32 v103, v123
	v_mov_b32_e32 v102, v123
	v_mov_b32_e32 v101, v123
	v_mov_b32_e32 v100, v123
	v_mov_b32_e32 v99, v123
	v_mov_b32_e32 v98, v123
	v_mov_b32_e32 v97, v123
	v_mov_b32_e32 v96, v123
	v_mov_b32_e32 v87, v123
	v_mov_b32_e32 v86, v123
	v_mov_b32_e32 v85, v123
	v_mov_b32_e32 v84, v123
	v_mov_b32_e32 v83, v123
	v_mov_b32_e32 v82, v123
	v_mov_b32_e32 v81, v123
	v_mov_b32_e32 v80, v123
	v_mov_b32_e32 v71, v123
	v_mov_b32_e32 v70, v123
	v_mov_b32_e32 v69, v123
	v_mov_b32_e32 v68, v123
	v_mov_b32_e32 v67, v123
	v_mov_b32_e32 v66, v123
	v_mov_b32_e32 v65, v123
	v_mov_b32_e32 v64, v123
	v_mov_b32_e32 v63, v123
	v_mov_b32_e32 v62, v123
	v_mov_b32_e32 v61, v123
	v_mov_b32_e32 v60, v123
	v_mov_b32_e32 v59, v123
	v_mov_b32_e32 v58, v123
	v_mov_b32_e32 v57, v123
	v_mov_b32_e32 v56, v123
	v_mov_b32_e32 v47, v123
	v_mov_b32_e32 v46, v123
	v_mov_b32_e32 v45, v123
	v_mov_b32_e32 v44, v123
	v_mov_b32_e32 v43, v123
	v_mov_b32_e32 v42, v123
	v_mov_b32_e32 v41, v123
	v_mov_b32_e32 v40, v123
	v_mov_b32_e32 v31, v123
	v_mov_b32_e32 v30, v123
	v_mov_b32_e32 v29, v123
	v_mov_b32_e32 v28, v123
	v_mov_b32_e32 v27, v123
	v_mov_b32_e32 v26, v123
	v_mov_b32_e32 v25, v123
	v_mov_b32_e32 v24, v123
	v_mov_b32_e32 v15, v123
	v_mov_b32_e32 v14, v123
	v_mov_b32_e32 v13, v123
	v_mov_b32_e32 v12, v123
	v_mov_b32_e32 v11, v123
	v_mov_b32_e32 v10, v123
	v_mov_b32_e32 v9, v123
	v_mov_b32_e32 v8, v123
	v_mov_b32_e32 v55, v123
	v_mov_b32_e32 v54, v123
	v_mov_b32_e32 v53, v123
	v_mov_b32_e32 v52, v123
	v_mov_b32_e32 v51, v123
	v_mov_b32_e32 v50, v123
	v_mov_b32_e32 v49, v123
	v_mov_b32_e32 v48, v123
	v_mov_b32_e32 v39, v123
	v_mov_b32_e32 v38, v123
	v_mov_b32_e32 v37, v123
	v_mov_b32_e32 v36, v123
	v_mov_b32_e32 v35, v123
	v_mov_b32_e32 v34, v123
	v_mov_b32_e32 v33, v123
	v_mov_b32_e32 v32, v123
	v_mov_b32_e32 v23, v123
	v_mov_b32_e32 v22, v123
	v_mov_b32_e32 v21, v123
	v_mov_b32_e32 v20, v123
	v_mov_b32_e32 v19, v123
	v_mov_b32_e32 v18, v123
	v_mov_b32_e32 v17, v123
	v_mov_b32_e32 v16, v123
	v_mov_b32_e32 v7, v123
	v_mov_b32_e32 v6, v123
	v_mov_b32_e32 v5, v123
	v_mov_b32_e32 v4, v123
	v_mov_b32_e32 v3, v123
	v_mov_b32_e32 v2, v123
	v_mov_b32_e32 v1, v123
	v_mov_b32_e32 v0, v123
	s_cbranch_vccnz .LBB0_1735
.Lzskip_10:
	s_and_b64 s[40:41], s[4:5], exec
	s_cselect_b32 s25, s29, s39
	s_cselect_b32 s27, s28, s38
	s_cselect_b32 s35, s31, s37
	s_cselect_b32 s59, s30, s36
	s_add_u32 s60, s36, 0x100
	s_addc_u32 s61, s37, 0
	s_add_u32 s36, s38, 0x40080
	v_mov_b32_e32 v0, 0
	s_addc_u32 s37, s39, 0
	s_mov_b32 s38, 0
	v_mov_b32_e32 v1, v0
	v_mov_b32_e32 v2, v0
	v_mov_b32_e32 v3, v0
	v_mov_b32_e32 v4, v0
	v_mov_b32_e32 v5, v0
	v_mov_b32_e32 v6, v0
	v_mov_b32_e32 v7, v0
	v_mov_b32_e32 v16, v0
	v_mov_b32_e32 v17, v0
	v_mov_b32_e32 v18, v0
	v_mov_b32_e32 v19, v0
	v_mov_b32_e32 v20, v0
	v_mov_b32_e32 v21, v0
	v_mov_b32_e32 v22, v0
	v_mov_b32_e32 v23, v0
	v_mov_b32_e32 v32, v0
	v_mov_b32_e32 v33, v0
	v_mov_b32_e32 v34, v0
	v_mov_b32_e32 v35, v0
	v_mov_b32_e32 v36, v0
	v_mov_b32_e32 v37, v0
	v_mov_b32_e32 v38, v0
	v_mov_b32_e32 v39, v0
	v_mov_b32_e32 v48, v0
	v_mov_b32_e32 v49, v0
	v_mov_b32_e32 v50, v0
	v_mov_b32_e32 v51, v0
	v_mov_b32_e32 v52, v0
	v_mov_b32_e32 v53, v0
	v_mov_b32_e32 v54, v0
	v_mov_b32_e32 v55, v0
	v_mov_b32_e32 v8, v0
	v_mov_b32_e32 v9, v0
	v_mov_b32_e32 v10, v0
	v_mov_b32_e32 v11, v0
	v_mov_b32_e32 v12, v0
	v_mov_b32_e32 v13, v0
	v_mov_b32_e32 v14, v0
	v_mov_b32_e32 v15, v0
	v_mov_b32_e32 v24, v0
	v_mov_b32_e32 v25, v0
	v_mov_b32_e32 v26, v0
	v_mov_b32_e32 v27, v0
	v_mov_b32_e32 v28, v0
	v_mov_b32_e32 v29, v0
	v_mov_b32_e32 v30, v0
	v_mov_b32_e32 v31, v0
	v_mov_b32_e32 v40, v0
	v_mov_b32_e32 v41, v0
	v_mov_b32_e32 v42, v0
	v_mov_b32_e32 v43, v0
	v_mov_b32_e32 v44, v0
	v_mov_b32_e32 v45, v0
	v_mov_b32_e32 v46, v0
	v_mov_b32_e32 v47, v0
	v_mov_b32_e32 v56, v0
	v_mov_b32_e32 v57, v0
	v_mov_b32_e32 v58, v0
	v_mov_b32_e32 v59, v0
	v_mov_b32_e32 v60, v0
	v_mov_b32_e32 v61, v0
	v_mov_b32_e32 v62, v0
	v_mov_b32_e32 v63, v0
	v_mov_b32_e32 v64, v0
	v_mov_b32_e32 v65, v0
	v_mov_b32_e32 v66, v0
	v_mov_b32_e32 v67, v0
	v_mov_b32_e32 v68, v0
	v_mov_b32_e32 v69, v0
	v_mov_b32_e32 v70, v0
	v_mov_b32_e32 v71, v0
	v_mov_b32_e32 v80, v0
	v_mov_b32_e32 v81, v0
	v_mov_b32_e32 v82, v0
	v_mov_b32_e32 v83, v0
	v_mov_b32_e32 v84, v0
	v_mov_b32_e32 v85, v0
	v_mov_b32_e32 v86, v0
	v_mov_b32_e32 v87, v0
	v_mov_b32_e32 v96, v0
	v_mov_b32_e32 v97, v0
	v_mov_b32_e32 v98, v0
	v_mov_b32_e32 v99, v0
	v_mov_b32_e32 v100, v0
	v_mov_b32_e32 v101, v0
	v_mov_b32_e32 v102, v0
	v_mov_b32_e32 v103, v0
	v_mov_b32_e32 v112, v0
	v_mov_b32_e32 v113, v0
	v_mov_b32_e32 v114, v0
	v_mov_b32_e32 v115, v0
	v_mov_b32_e32 v116, v0
	v_mov_b32_e32 v117, v0
	v_mov_b32_e32 v118, v0
	v_mov_b32_e32 v119, v0
	v_mov_b32_e32 v72, v0
	v_mov_b32_e32 v73, v0
	v_mov_b32_e32 v74, v0
	v_mov_b32_e32 v75, v0
	v_mov_b32_e32 v76, v0
	v_mov_b32_e32 v77, v0
	v_mov_b32_e32 v78, v0
	v_mov_b32_e32 v79, v0
	v_mov_b32_e32 v88, v0
	v_mov_b32_e32 v89, v0
	v_mov_b32_e32 v90, v0
	v_mov_b32_e32 v91, v0
	v_mov_b32_e32 v92, v0
	v_mov_b32_e32 v93, v0
	v_mov_b32_e32 v94, v0
	v_mov_b32_e32 v95, v0
	v_mov_b32_e32 v104, v0
	v_mov_b32_e32 v105, v0
	v_mov_b32_e32 v106, v0
	v_mov_b32_e32 v107, v0
	v_mov_b32_e32 v108, v0
	v_mov_b32_e32 v109, v0
	v_mov_b32_e32 v110, v0
	v_mov_b32_e32 v111, v0
	v_mov_b32_e32 v124, v0
	v_mov_b32_e32 v125, v0
	v_mov_b32_e32 v126, v0
	v_mov_b32_e32 v127, v0
	v_mov_b32_e32 v120, v0
	v_mov_b32_e32 v121, v0
	v_mov_b32_e32 v122, v0
	v_mov_b32_e32 v123, v0

; template <class Epi>
; __device__ __forceinline__ void gemm_phase(LAS unsigned char* lds, const int tid, const Gemm g, const StaticOrder& S, const Epi& E) {
;     ...
;         const bool has_next = S.next(ui + 1, nxt);
;         const char* nA = has_next ? (const char*)g.A + (size_t)nxt.pm * tstepA + (size_t)(nxt.pn >> g.a_grp_shift) * g.a_grp_bytes : cA;
;         const char* nB = has_next ? (const char*)g.Bt + (size_t)nxt.pn * tstepB : cB;
;         for (int t = 0; t < nt; t += 2) {
;             const bool last = (t == nt - 2);
;             const char* a1 = cA + (size_t)(t + 1) * kstep;
;             const char* a2 = last ? nA : cA + (size_t)(t + 2) * kstep; const char* b2 = last ? nB : cB + (size_t)(t + 2) * kstep;
;             const char* a3 = a2 + kstep; const char* b3 = b2 + kstep;
;             if constexpr (Epi::SS_LDS) { if (last) {
;                 const char* sp = (const char*)E.ss + (size_t)cur.pm * (256 * 64) + (size_t)tid * 16;
;     ...
; #pragma unroll
;         for (int a = 0; a < 2; ++a)
; #pragma unroll
;             for (int b = 0; b < 2; ++b)
; #pragma unroll
;                 for (int m = 0; m < 4; ++m)
; #pragma unroll
;                     for (int n = 0; n < 2; ++n) acc[a][b][m][n] = (f32x4){0.f, 0.f, 0.f, 0.f};
.LBB0_2034:
	s_ashr_i32 s21, s20, 31
	s_lshl_b64 s[22:23], s[20:21], 19
	s_add_u32 s22, s2, s22
	s_addc_u32 s23, s3, s23
	s_ashr_i32 s19, s18, 31
	s_lshl_b64 s[24:25], s[18:19], 19
	s_add_u32 s24, s37, s24
	v_mov_b32_e32 v127, 0
	s_addc_u32 s25, s38, s25
	s_andn2_b64 vcc, exec, s[14:15]
	s_cbranch_vccz .Lzskip_13
	v_mov_b32_e32 v126, v127
	v_mov_b32_e32 v125, v127
	v_mov_b32_e32 v124, v127
	v_mov_b32_e32 v123, v127
	v_mov_b32_e32 v122, v127
	v_mov_b32_e32 v121, v127
	v_mov_b32_e32 v120, v127
	v_mov_b32_e32 v111, v127
	v_mov_b32_e32 v110, v127
	v_mov_b32_e32 v109, v127
	v_mov_b32_e32 v108, v127
	v_mov_b32_e32 v107, v127
	v_mov_b32_e32 v106, v127
	v_mov_b32_e32 v105, v127
	v_mov_b32_e32 v104, v127
	v_mov_b32_e32 v95, v127
	v_mov_b32_e32 v94, v127
	v_mov_b32_e32 v93, v127
	v_mov_b32_e32 v92, v127
	v_mov_b32_e32 v91, v127
	v_mov_b32_e32 v90, v127
	v_mov_b32_e32 v89, v127
	v_mov_b32_e32 v88, v127
	v_mov_b32_e32 v79, v127
	v_mov_b32_e32 v78, v127
	v_mov_b32_e32 v77, v127
	v_mov_b32_e32 v76, v127
	v_mov_b32_e32 v75, v127
	v_mov_b32_e32 v74, v127
	v_mov_b32_e32 v73, v127
	v_mov_b32_e32 v72, v127
	v_mov_b32_e32 v119, v127
	v_mov_b32_e32 v118, v127
	v_mov_b32_e32 v117, v127
	v_mov_b32_e32 v116, v127
	v_mov_b32_e32 v115, v127
	v_mov_b32_e32 v114, v127
	v_mov_b32_e32 v113, v127
	v_mov_b32_e32 v112, v127
	v_mov_b32_e32 v103, v127
	v_mov_b32_e32 v102, v127
	v_mov_b32_e32 v101, v127
	v_mov_b32_e32 v100, v127
	v_mov_b32_e32 v99, v127
	v_mov_b32_e32 v98, v127
	v_mov_b32_e32 v97, v127
	v_mov_b32_e32 v96, v127
	v_mov_b32_e32 v87, v127
	v_mov_b32_e32 v86, v127
	v_mov_b32_e32 v85, v127
	v_mov_b32_e32 v84, v127
	v_mov_b32_e32 v83, v127
	v_mov_b32_e32 v82, v127
	v_mov_b32_e32 v81, v127
	v_mov_b32_e32 v80, v127
	v_mov_b32_e32 v71, v127
	v_mov_b32_e32 v70, v127
	v_mov_b32_e32 v69, v127
	v_mov_b32_e32 v68, v127
	v_mov_b32_e32 v67, v127
	v_mov_b32_e32 v66, v127
	v_mov_b32_e32 v65, v127
	v_mov_b32_e32 v64, v127
	v_mov_b32_e32 v63, v127
	v_mov_b32_e32 v62, v127
	v_mov_b32_e32 v61, v127
	v_mov_b32_e32 v60, v127
	v_mov_b32_e32 v59, v127
	v_mov_b32_e32 v58, v127
	v_mov_b32_e32 v57, v127
	v_mov_b32_e32 v56, v127
	v_mov_b32_e32 v47, v127
	v_mov_b32_e32 v46, v127
	v_mov_b32_e32 v45, v127
	v_mov_b32_e32 v44, v127
	v_mov_b32_e32 v43, v127
	v_mov_b32_e32 v42, v127
	v_mov_b32_e32 v41, v127
	v_mov_b32_e32 v40, v127
	v_mov_b32_e32 v31, v127
	v_mov_b32_e32 v30, v127
	v_mov_b32_e32 v29, v127
	v_mov_b32_e32 v28, v127
	v_mov_b32_e32 v27, v127
	v_mov_b32_e32 v26, v127
	v_mov_b32_e32 v25, v127
	v_mov_b32_e32 v24, v127
	v_mov_b32_e32 v15, v127
	v_mov_b32_e32 v14, v127
	v_mov_b32_e32 v13, v127
	v_mov_b32_e32 v12, v127
	v_mov_b32_e32 v11, v127
	v_mov_b32_e32 v10, v127
	v_mov_b32_e32 v9, v127
	v_mov_b32_e32 v8, v127
	v_mov_b32_e32 v55, v127
	v_mov_b32_e32 v54, v127
	v_mov_b32_e32 v53, v127
	v_mov_b32_e32 v52, v127
	v_mov_b32_e32 v51, v127
	v_mov_b32_e32 v50, v127
	v_mov_b32_e32 v49, v127
	v_mov_b32_e32 v48, v127
	v_mov_b32_e32 v39, v127
	v_mov_b32_e32 v38, v127
	v_mov_b32_e32 v37, v127
	v_mov_b32_e32 v36, v127
	v_mov_b32_e32 v35, v127
	v_mov_b32_e32 v34, v127
	v_mov_b32_e32 v33, v127
	v_mov_b32_e32 v32, v127
	v_mov_b32_e32 v23, v127
	v_mov_b32_e32 v22, v127
	v_mov_b32_e32 v21, v127
	v_mov_b32_e32 v20, v127
	v_mov_b32_e32 v19, v127
	v_mov_b32_e32 v18, v127
	v_mov_b32_e32 v17, v127
	v_mov_b32_e32 v16, v127
	v_mov_b32_e32 v7, v127
	v_mov_b32_e32 v6, v127
	v_mov_b32_e32 v5, v127
	v_mov_b32_e32 v4, v127
	v_mov_b32_e32 v3, v127
	v_mov_b32_e32 v2, v127
	v_mov_b32_e32 v1, v127
	v_mov_b32_e32 v0, v127
	s_cbranch_vccnz .LBB0_2039
.Lzskip_13:
	s_and_b64 s[34:35], s[0:1], exec
	s_cselect_b32 s19, s23, s31
	s_cselect_b32 s21, s22, s30
	s_cselect_b32 s52, s25, s29
	s_cselect_b32 s53, s24, s28
	s_ashr_i32 s27, s26, 31
	s_lshl_b64 s[34:35], s[26:27], 14
	s_add_u32 s27, s28, 0x100
	s_addc_u32 s54, s29, 0
	v_lshl_add_u64 v[128:129], v[192:193], 0, s[34:35]
	s_add_u32 s28, s30, 0x40080
	v_mov_b32_e32 v0, 0
	v_lshl_add_u64 v[130:131], v[128:129], 0, s[6:7]
	s_addc_u32 s29, s31, 0
	s_mov_b32 s55, 0
	v_mov_b32_e32 v1, v0
	v_mov_b32_e32 v2, v0
	v_mov_b32_e32 v3, v0
	v_mov_b32_e32 v4, v0
	v_mov_b32_e32 v5, v0
	v_mov_b32_e32 v6, v0
	v_mov_b32_e32 v7, v0
	v_mov_b32_e32 v16, v0
	v_mov_b32_e32 v17, v0
	v_mov_b32_e32 v18, v0
	v_mov_b32_e32 v19, v0
	v_mov_b32_e32 v20, v0
	v_mov_b32_e32 v21, v0
	v_mov_b32_e32 v22, v0
	v_mov_b32_e32 v23, v0
	v_mov_b32_e32 v32, v0
	v_mov_b32_e32 v33, v0
	v_mov_b32_e32 v34, v0
	v_mov_b32_e32 v35, v0
	v_mov_b32_e32 v36, v0
	v_mov_b32_e32 v37, v0
	v_mov_b32_e32 v38, v0
	v_mov_b32_e32 v39, v0
	v_mov_b32_e32 v48, v0
	v_mov_b32_e32 v49, v0
	v_mov_b32_e32 v50, v0
	v_mov_b32_e32 v51, v0
	v_mov_b32_e32 v52, v0
	v_mov_b32_e32 v53, v0
	v_mov_b32_e32 v54, v0
	v_mov_b32_e32 v55, v0
	v_mov_b32_e32 v8, v0
	v_mov_b32_e32 v9, v0
	v_mov_b32_e32 v10, v0
	v_mov_b32_e32 v11, v0
	v_mov_b32_e32 v12, v0
	v_mov_b32_e32 v13, v0
	v_mov_b32_e32 v14, v0
	v_mov_b32_e32 v15, v0
	v_mov_b32_e32 v24, v0
	v_mov_b32_e32 v25, v0
	v_mov_b32_e32 v26, v0
	v_mov_b32_e32 v27, v0
	v_mov_b32_e32 v28, v0
	v_mov_b32_e32 v29, v0
	v_mov_b32_e32 v30, v0
	v_mov_b32_e32 v31, v0
	v_mov_b32_e32 v40, v0
	v_mov_b32_e32 v41, v0
	v_mov_b32_e32 v42, v0
	v_mov_b32_e32 v43, v0
	v_mov_b32_e32 v44, v0
	v_mov_b32_e32 v45, v0
	v_mov_b32_e32 v46, v0
	v_mov_b32_e32 v47, v0
	v_mov_b32_e32 v56, v0
	v_mov_b32_e32 v57, v0
	v_mov_b32_e32 v58, v0
	v_mov_b32_e32 v59, v0
	v_mov_b32_e32 v60, v0
	v_mov_b32_e32 v61, v0
	v_mov_b32_e32 v62, v0
	v_mov_b32_e32 v63, v0
	v_mov_b32_e32 v64, v0
	v_mov_b32_e32 v65, v0
	v_mov_b32_e32 v66, v0
	v_mov_b32_e32 v67, v0
	v_mov_b32_e32 v68, v0
	v_mov_b32_e32 v69, v0
	v_mov_b32_e32 v70, v0
	v_mov_b32_e32 v71, v0
	v_mov_b32_e32 v80, v0
	v_mov_b32_e32 v81, v0
	v_mov_b32_e32 v82, v0
	v_mov_b32_e32 v83, v0
	v_mov_b32_e32 v84, v0
	v_mov_b32_e32 v85, v0
	v_mov_b32_e32 v86, v0
	v_mov_b32_e32 v87, v0
	v_mov_b32_e32 v96, v0
	v_mov_b32_e32 v97, v0
	v_mov_b32_e32 v98, v0
	v_mov_b32_e32 v99, v0
	v_mov_b32_e32 v100, v0
	v_mov_b32_e32 v101, v0
	v_mov_b32_e32 v102, v0
	v_mov_b32_e32 v103, v0
	v_mov_b32_e32 v112, v0
	v_mov_b32_e32 v113, v0
	v_mov_b32_e32 v114, v0
	v_mov_b32_e32 v115, v0
	v_mov_b32_e32 v116, v0
	v_mov_b32_e32 v117, v0
	v_mov_b32_e32 v118, v0
	v_mov_b32_e32 v119, v0
	v_mov_b32_e32 v72, v0
	v_mov_b32_e32 v73, v0
	v_mov_b32_e32 v74, v0
	v_mov_b32_e32 v75, v0
	v_mov_b32_e32 v76, v0
	v_mov_b32_e32 v77, v0
	v_mov_b32_e32 v78, v0
	v_mov_b32_e32 v79, v0
	v_mov_b32_e32 v88, v0
	v_mov_b32_e32 v89, v0
	v_mov_b32_e32 v90, v0
	v_mov_b32_e32 v91, v0
	v_mov_b32_e32 v92, v0
	v_mov_b32_e32 v93, v0
	v_mov_b32_e32 v94, v0
	v_mov_b32_e32 v95, v0
	v_mov_b32_e32 v104, v0
	v_mov_b32_e32 v105, v0
	v_mov_b32_e32 v106, v0
	v_mov_b32_e32 v107, v0
	v_mov_b32_e32 v108, v0
	v_mov_b32_e32 v109, v0
	v_mov_b32_e32 v110, v0
	v_mov_b32_e32 v111, v0
	v_mov_b32_e32 v120, v0
	v_mov_b32_e32 v121, v0
	v_mov_b32_e32 v122, v0
	v_mov_b32_e32 v123, v0
	v_mov_b32_e32 v124, v0
	v_mov_b32_e32 v125, v0
	v_mov_b32_e32 v126, v0
	v_mov_b32_e32 v127, v0
	s_branch .LBB0_2037
